# v40 + static priority raise for the leading half (waves 0-3) from its align barrier through the epilogue and next unit head
# baseline (speedup 1.0000x reference)
; #define PG8_STAGE(bufoff, gbase, voff) do { _Pragma("unroll") for (int _i = 0; _i < 2; ++_i) \
;         __builtin_amdgcn_global_load_lds((const unsigned*)((const char*)(gbase) + (voff)[_i]), (PG8_LAS unsigned*)(lds + (bufoff) + ldsw + _i * 8192), 16, 0, 0); } while (0)
; #define PG8_LDA(dst, b, h) do { _Pragma("unroll") for (int m = 0; m < 4; ++m) _Pragma("unroll") for (int k = 0; k < 2; ++k) dst[m][k] = *(const PG8_LAS bf16x8*)(lds + PG8_SA(b, h) + aoff + m * 2048 + k * 1024); } while (0)
; #define PG8_LDB(dst, b, h) do { _Pragma("unroll") for (int n = 0; n < 2; ++n) _Pragma("unroll") for (int k = 0; k < 2; ++k) dst[n][k] = *(const PG8_LAS bf16x8*)(lds + PG8_SB(b, h) + boff + n * 2048 + k * 1024); } while (0)
; #define PG8_MMA(ai, bj, At, Bt) do { __builtin_amdgcn_s_setprio(1); _Pragma("unroll") for (int m = 0; m < 4; ++m) _Pragma("unroll") for (int n = 0; n < 2; ++n) _Pragma("unroll") for (int k = 0; k < 2; ++k) \
;         acc[ai][bj][m][n] = __builtin_amdgcn_mfma_f32_16x16x32_bf16(Bt[n][k], At[m][k], acc[ai][bj][m][n], 0, 0, 0); __builtin_amdgcn_s_setprio(0); } while (0)
; #define PG8_WAIT_V(n) asm volatile("s_waitcnt vmcnt(" #n ")" ::: "memory")
; #define PG8_WAIT_L(n) asm volatile("s_waitcnt lgkmcnt(" #n ")" ::: "memory")
; #define PG8_BAR __builtin_amdgcn_s_barrier()
; #define PG8_SCHED __builtin_amdgcn_sched_barrier(0)
; template <class Epi, class Sched, bool ALIGN_EPI = false, bool SP2 = false>
; __device__ __forceinline__ void gemm_phase(PG8_LAS unsigned char* lds, const Gemm g, const Sched& S, const Epi& E, int tid_in) {
;     ...
;             PG8_LDB(B0, 0, 0); PG8_LDB(B1, 0, 1); PG8_SCHED; PG8_LDA(At, 0, 0); PG8_STAGE(PG8_SA(1, 1), a1 + hstep, voffA);
;             PG8_WAIT_V(8); PG8_WAIT_L(0); PG8_BAR; PG8_MMA(0, 0, At, B0); PG8_MMA(0, 1, At, B1); PG8_BAR; PG8_SCHED;
;             PG8_LDA(At, 0, 1); PG8_STAGE(PG8_SB(0, 0), b2, voffB); PG8_STAGE(PG8_SB(0, 1), b2 + hstep, voffB); PG8_STAGE(PG8_SA(0, 0), a2, voffA);
;             PG8_WAIT_V(8); PG8_WAIT_L(0); PG8_BAR; PG8_MMA(1, 0, At, B0); PG8_MMA(1, 1, At, B1); PG8_BAR; PG8_SCHED;
.LBB0_158:
	v_or_b32_e32 v32, 0x10000, v194
	v_add_u32_e32 v36, 0x10400, v194
	v_add_u32_e32 v44, 0x10800, v194
	v_add_u32_e32 v48, 0x10c00, v194
	v_or_b32_e32 v81, 0x14000, v194
	v_add_u32_e32 v162, 0x14400, v194
	ds_read_b128 v[32:35], v32
	ds_read_b128 v[36:39], v36
	ds_read_b128 v[44:47], v44
	ds_read_b128 v[48:51], v48
	ds_read_b128 v[158:161], v81
	ds_read_b128 v[162:165], v162
	v_add_u32_e32 v81, 0x14800, v194
	v_add_u32_e32 v170, 0x14c00, v194
	ds_read_b128 v[166:169], v81
	ds_read_b128 v[170:173], v170
	s_add_u32 s29, s84, 0xfffc0080
	s_addc_u32 s31, s85, -1
	s_cmp_eq_u32 s27, 12
	s_cselect_b32 s89, s21, s31
	s_cselect_b32 s88, s22, s29
	s_cselect_b32 s87, s23, s26
	s_cselect_b32 s86, s24, s25
	s_mov_b32 m0, s63
	v_lshl_add_u64 v[174:175], s[84:85], 0, v[154:155]
	ds_read_b128 v[182:185], v177
	ds_read_b128 v[200:203], v177 offset:1024
	ds_read_b128 v[204:207], v177 offset:2048
	ds_read_b128 v[208:211], v177 offset:3072
	ds_read_b128 v[212:215], v177 offset:4096
	ds_read_b128 v[216:219], v177 offset:5120
	ds_read_b128 v[226:229], v177 offset:6144
	ds_read_b128 v[232:235], v177 offset:7168
	global_load_lds_dwordx4 v[174:175], off
	v_lshl_add_u64 v[174:175], s[84:85], 0, v[156:157]
	s_mov_b32 m0, s62
	s_nop 0
	global_load_lds_dwordx4 v[174:175], off
	s_waitcnt vmcnt(8)
	s_waitcnt lgkmcnt(0)
	s_barrier
	s_setprio 1
	s_waitcnt lgkmcnt(0)
	v_mfma_f32_16x16x32_bf16 v[142:145], v[32:35], v[182:185], v[142:145]
	v_mfma_f32_16x16x32_bf16 v[138:141], v[44:47], v[182:185], v[138:141]
	v_mfma_f32_16x16x32_bf16 v[126:129], v[32:35], v[204:207], v[126:129]
	v_mfma_f32_16x16x32_bf16 v[122:125], v[44:47], v[204:207], v[122:125]
	v_mfma_f32_16x16x32_bf16 v[110:113], v[32:35], v[212:215], v[110:113]
	v_mfma_f32_16x16x32_bf16 v[106:109], v[44:47], v[212:215], v[106:109]
	v_mfma_f32_16x16x32_bf16 v[94:97], v[32:35], v[226:229], v[94:97]
	v_mfma_f32_16x16x32_bf16 v[90:93], v[44:47], v[226:229], v[90:93]
	v_mfma_f32_16x16x32_bf16 v[142:145], v[36:39], v[200:203], v[142:145]
	v_mfma_f32_16x16x32_bf16 v[138:141], v[48:51], v[200:203], v[138:141]
	v_mfma_f32_16x16x32_bf16 v[126:129], v[36:39], v[208:211], v[126:129]
	v_mfma_f32_16x16x32_bf16 v[122:125], v[48:51], v[208:211], v[122:125]
	v_mfma_f32_16x16x32_bf16 v[110:113], v[36:39], v[216:219], v[110:113]
	v_mfma_f32_16x16x32_bf16 v[106:109], v[48:51], v[216:219], v[106:109]
	v_mfma_f32_16x16x32_bf16 v[94:97], v[36:39], v[232:235], v[94:97]
	v_mfma_f32_16x16x32_bf16 v[90:93], v[48:51], v[232:235], v[90:93]
	s_setprio 0
	s_setprio 1
	v_mfma_f32_16x16x32_bf16 v[134:137], v[158:161], v[182:185], v[134:137]
	v_mfma_f32_16x16x32_bf16 v[130:133], v[166:169], v[182:185], v[130:133]
	v_mfma_f32_16x16x32_bf16 v[118:121], v[158:161], v[204:207], v[118:121]
	v_mfma_f32_16x16x32_bf16 v[114:117], v[166:169], v[204:207], v[114:117]
	v_mfma_f32_16x16x32_bf16 v[102:105], v[158:161], v[212:215], v[102:105]
	v_mfma_f32_16x16x32_bf16 v[98:101], v[166:169], v[212:215], v[98:101]
	v_mfma_f32_16x16x32_bf16 v[86:89], v[158:161], v[226:229], v[86:89]
	v_mfma_f32_16x16x32_bf16 v[82:85], v[166:169], v[226:229], v[82:85]
	v_mfma_f32_16x16x32_bf16 v[134:137], v[162:165], v[200:203], v[134:137]
	v_mfma_f32_16x16x32_bf16 v[130:133], v[170:173], v[200:203], v[130:133]
	v_mfma_f32_16x16x32_bf16 v[118:121], v[162:165], v[208:211], v[118:121]
	v_mfma_f32_16x16x32_bf16 v[114:117], v[170:173], v[208:211], v[114:117]
	v_mfma_f32_16x16x32_bf16 v[102:105], v[162:165], v[216:219], v[102:105]
	v_mfma_f32_16x16x32_bf16 v[98:101], v[170:173], v[216:219], v[98:101]
	v_mfma_f32_16x16x32_bf16 v[86:89], v[162:165], v[232:235], v[86:89]
	s_barrier
	v_mfma_f32_16x16x32_bf16 v[82:85], v[170:173], v[232:235], v[82:85]
	s_setprio 0
	s_mov_b32 m0, s43
	v_lshl_add_u64 v[174:175], s[86:87], 0, v[148:149]
	s_add_u32 s58, s86, 0x40000
	ds_read_b128 v[182:185], v177 offset:16384
	ds_read_b128 v[200:203], v177 offset:17408
	ds_read_b128 v[204:207], v177 offset:18432
	ds_read_b128 v[208:211], v177 offset:19456
	ds_read_b128 v[212:215], v177 offset:20480
	ds_read_b128 v[216:219], v177 offset:21504
	ds_read_b128 v[226:229], v177 offset:22528
	ds_read_b128 v[232:235], v177 offset:23552
	global_load_lds_dwordx4 v[174:175], off
	v_lshl_add_u64 v[178:179], s[86:87], 0, v[152:153]
	s_mov_b32 m0, s92
	s_addc_u32 s59, s87, 0
	global_load_lds_dwordx4 v[178:179], off
	v_lshl_add_u64 v[180:181], s[58:59], 0, v[148:149]
	s_mov_b32 m0, s93
	v_lshl_add_u64 v[236:237], s[88:89], 0, v[150:151]
	global_load_lds_dwordx4 v[180:181], off
	v_lshl_add_u64 v[180:181], s[58:59], 0, v[152:153]
	s_mov_b32 m0, s94
	s_nop 0
	global_load_lds_dwordx4 v[180:181], off
	v_lshl_add_u64 v[180:181], s[88:89], 0, v[146:147]
	s_mov_b32 m0, s70
	s_nop 0
	global_load_lds_dwordx4 v[180:181], off
	s_mov_b32 m0, s95
	s_nop 0
	global_load_lds_dwordx4 v[236:237], off
	s_waitcnt vmcnt(8)
	s_waitcnt lgkmcnt(0)
	s_barrier
; #define PG8_STAGE(bufoff, gbase, voff) do { _Pragma("unroll") for (int _i = 0; _i < 2; ++_i) \
;         __builtin_amdgcn_global_load_lds((const unsigned*)((const char*)(gbase) + (voff)[_i]), (PG8_LAS unsigned*)(lds + (bufoff) + ldsw + _i * 8192), 16, 0, 0); } while (0)
; #define PG8_LDA(dst, b, h) do { _Pragma("unroll") for (int m = 0; m < 4; ++m) _Pragma("unroll") for (int k = 0; k < 2; ++k) dst[m][k] = *(const PG8_LAS bf16x8*)(lds + PG8_SA(b, h) + aoff + m * 2048 + k * 1024); } while (0)
; #define PG8_LDB(dst, b, h) do { _Pragma("unroll") for (int n = 0; n < 2; ++n) _Pragma("unroll") for (int k = 0; k < 2; ++k) dst[n][k] = *(const PG8_LAS bf16x8*)(lds + PG8_SB(b, h) + boff + n * 2048 + k * 1024); } while (0)
; #define PG8_MMA(ai, bj, At, Bt) do { __builtin_amdgcn_s_setprio(1); _Pragma("unroll") for (int m = 0; m < 4; ++m) _Pragma("unroll") for (int n = 0; n < 2; ++n) _Pragma("unroll") for (int k = 0; k < 2; ++k) \
;         acc[ai][bj][m][n] = __builtin_amdgcn_mfma_f32_16x16x32_bf16(Bt[n][k], At[m][k], acc[ai][bj][m][n], 0, 0, 0); __builtin_amdgcn_s_setprio(0); } while (0)
; #define PG8_WAIT_V(n) asm volatile("s_waitcnt vmcnt(" #n ")" ::: "memory")
; #define PG8_WAIT_L(n) asm volatile("s_waitcnt lgkmcnt(" #n ")" ::: "memory")
; #define PG8_BAR __builtin_amdgcn_s_barrier()
; #define PG8_SCHED __builtin_amdgcn_sched_barrier(0)
; template <class Epi, class Sched, bool ALIGN_EPI = false, bool SP2 = false>
; __device__ __forceinline__ void gemm_phase(PG8_LAS unsigned char* lds, const Gemm g, const Sched& S, const Epi& E, int tid_in) {
;     ...
;             PG8_WAIT_V(8); PG8_WAIT_L(0); PG8_BAR; PG8_MMA(1, 0, At, B0); PG8_MMA(1, 1, At, B1); PG8_BAR; PG8_SCHED;
;             PG8_LDB(B0, 1, 0); PG8_LDB(B1, 1, 1); PG8_SCHED; PG8_LDA(At, 1, 0); PG8_STAGE(PG8_SA(0, 1), a2 + hstep, voffA);
;             PG8_WAIT_V(8); PG8_WAIT_L(0); PG8_BAR; PG8_MMA(0, 0, At, B0); PG8_MMA(0, 1, At, B1); PG8_BAR; PG8_SCHED;
	s_setprio 1
	s_waitcnt lgkmcnt(0)
	v_mfma_f32_16x16x32_bf16 v[76:79], v[32:35], v[182:185], v[76:79]
	v_mfma_f32_16x16x32_bf16 v[72:75], v[44:47], v[182:185], v[72:75]
	v_mfma_f32_16x16x32_bf16 v[60:63], v[32:35], v[204:207], v[60:63]
	v_mfma_f32_16x16x32_bf16 v[56:59], v[44:47], v[204:207], v[56:59]
	v_mfma_f32_16x16x32_bf16 v[28:31], v[32:35], v[212:215], v[28:31]
	v_mfma_f32_16x16x32_bf16 v[24:27], v[44:47], v[212:215], v[24:27]
	v_mfma_f32_16x16x32_bf16 v[12:15], v[32:35], v[226:229], v[12:15]
	v_mfma_f32_16x16x32_bf16 v[8:11], v[44:47], v[226:229], v[8:11]
	v_mfma_f32_16x16x32_bf16 v[76:79], v[36:39], v[200:203], v[76:79]
	v_mfma_f32_16x16x32_bf16 v[72:75], v[48:51], v[200:203], v[72:75]
	v_mfma_f32_16x16x32_bf16 v[60:63], v[36:39], v[208:211], v[60:63]
	v_mfma_f32_16x16x32_bf16 v[56:59], v[48:51], v[208:211], v[56:59]
	v_mfma_f32_16x16x32_bf16 v[28:31], v[36:39], v[216:219], v[28:31]
	v_mfma_f32_16x16x32_bf16 v[24:27], v[48:51], v[216:219], v[24:27]
	v_mfma_f32_16x16x32_bf16 v[12:15], v[36:39], v[232:235], v[12:15]
	v_mfma_f32_16x16x32_bf16 v[8:11], v[48:51], v[232:235], v[8:11]
	s_setprio 0
	s_setprio 1
	v_mfma_f32_16x16x32_bf16 v[40:43], v[166:169], v[204:207], v[40:43]
	v_mfma_f32_16x16x32_bf16 v[20:23], v[158:161], v[212:215], v[20:23]
	v_mfma_f32_16x16x32_bf16 v[16:19], v[166:169], v[212:215], v[16:19]
	v_mfma_f32_16x16x32_bf16 v[4:7], v[158:161], v[226:229], v[4:7]
	v_mfma_f32_16x16x32_bf16 v[0:3], v[166:169], v[226:229], v[0:3]
	v_mfma_f32_16x16x32_bf16 v[32:35], v[158:161], v[182:185], v[68:71]
	v_mfma_f32_16x16x32_bf16 v[36:39], v[166:169], v[182:185], v[64:67]
	v_mfma_f32_16x16x32_bf16 v[44:47], v[158:161], v[204:207], v[52:55]
	v_mfma_f32_16x16x32_bf16 v[40:43], v[170:173], v[208:211], v[40:43]
	v_mfma_f32_16x16x32_bf16 v[20:23], v[162:165], v[216:219], v[20:23]
	v_mfma_f32_16x16x32_bf16 v[16:19], v[170:173], v[216:219], v[16:19]
	v_mfma_f32_16x16x32_bf16 v[4:7], v[162:165], v[232:235], v[4:7]
	v_mfma_f32_16x16x32_bf16 v[0:3], v[170:173], v[232:235], v[0:3]
	v_mfma_f32_16x16x32_bf16 v[32:35], v[162:165], v[200:203], v[32:35]
	v_mfma_f32_16x16x32_bf16 v[36:39], v[170:173], v[200:203], v[36:39]
	s_barrier
	v_mfma_f32_16x16x32_bf16 v[44:47], v[162:165], v[208:211], v[44:47]
	s_setprio 0
	v_or_b32_e32 v48, 0x18000, v194
	v_add_u32_e32 v52, 0x18400, v194
	v_add_u32_e32 v64, 0x18800, v194
	v_add_u32_e32 v68, 0x18c00, v194
	v_or_b32_e32 v81, 0x1c000, v194
	v_add_u32_e32 v162, 0x1c400, v194
	ds_read_b128 v[48:51], v48
	ds_read_b128 v[52:55], v52
	ds_read_b128 v[64:67], v64
	ds_read_b128 v[68:71], v68
	ds_read_b128 v[158:161], v81
	ds_read_b128 v[162:165], v162
	v_add_u32_e32 v81, 0x1c800, v194
	v_add_u32_e32 v170, 0x1cc00, v194
	ds_read_b128 v[166:169], v81
	ds_read_b128 v[170:173], v170
	s_add_u32 s58, s88, 0x40000
	s_addc_u32 s59, s89, 0
	s_mov_b32 m0, s57
	v_lshl_add_u64 v[238:239], s[58:59], 0, v[146:147]
	ds_read_b128 v[182:185], v177 offset:32768
	ds_read_b128 v[200:203], v177 offset:33792
	ds_read_b128 v[204:207], v177 offset:34816
	ds_read_b128 v[208:211], v177 offset:35840
	ds_read_b128 v[212:215], v177 offset:36864
	ds_read_b128 v[216:219], v177 offset:37888
	ds_read_b128 v[226:229], v177 offset:38912
	ds_read_b128 v[232:235], v177 offset:39936
	global_load_lds_dwordx4 v[238:239], off
	v_lshl_add_u64 v[238:239], s[58:59], 0, v[150:151]
	s_mov_b32 m0, s52
	s_nop 0
	global_load_lds_dwordx4 v[238:239], off
	s_waitcnt vmcnt(8)
	s_waitcnt lgkmcnt(0)
	s_barrier
	s_setprio 1
	s_waitcnt lgkmcnt(0)
	v_mfma_f32_16x16x32_bf16 v[142:145], v[48:51], v[182:185], v[142:145]
	v_mfma_f32_16x16x32_bf16 v[138:141], v[64:67], v[182:185], v[138:141]
	v_mfma_f32_16x16x32_bf16 v[126:129], v[48:51], v[204:207], v[126:129]
	v_mfma_f32_16x16x32_bf16 v[122:125], v[64:67], v[204:207], v[122:125]
	v_mfma_f32_16x16x32_bf16 v[110:113], v[48:51], v[212:215], v[110:113]
	v_mfma_f32_16x16x32_bf16 v[106:109], v[64:67], v[212:215], v[106:109]
	v_mfma_f32_16x16x32_bf16 v[94:97], v[48:51], v[226:229], v[94:97]
	v_mfma_f32_16x16x32_bf16 v[90:93], v[64:67], v[226:229], v[90:93]
	v_mfma_f32_16x16x32_bf16 v[142:145], v[52:55], v[200:203], v[142:145]
	v_mfma_f32_16x16x32_bf16 v[138:141], v[68:71], v[200:203], v[138:141]
	v_mfma_f32_16x16x32_bf16 v[126:129], v[52:55], v[208:211], v[126:129]
	v_mfma_f32_16x16x32_bf16 v[122:125], v[68:71], v[208:211], v[122:125]
	v_mfma_f32_16x16x32_bf16 v[110:113], v[52:55], v[216:219], v[110:113]
	v_mfma_f32_16x16x32_bf16 v[106:109], v[68:71], v[216:219], v[106:109]
	v_mfma_f32_16x16x32_bf16 v[94:97], v[52:55], v[232:235], v[94:97]
	v_mfma_f32_16x16x32_bf16 v[90:93], v[68:71], v[232:235], v[90:93]
	s_setprio 0
	s_setprio 1
	v_mfma_f32_16x16x32_bf16 v[134:137], v[158:161], v[182:185], v[134:137]
	v_mfma_f32_16x16x32_bf16 v[130:133], v[166:169], v[182:185], v[130:133]
	v_mfma_f32_16x16x32_bf16 v[118:121], v[158:161], v[204:207], v[118:121]
	v_mfma_f32_16x16x32_bf16 v[114:117], v[166:169], v[204:207], v[114:117]
	v_mfma_f32_16x16x32_bf16 v[102:105], v[158:161], v[212:215], v[102:105]
	v_mfma_f32_16x16x32_bf16 v[98:101], v[166:169], v[212:215], v[98:101]
	v_mfma_f32_16x16x32_bf16 v[86:89], v[158:161], v[226:229], v[86:89]
	v_mfma_f32_16x16x32_bf16 v[82:85], v[166:169], v[226:229], v[82:85]
	v_mfma_f32_16x16x32_bf16 v[134:137], v[162:165], v[200:203], v[134:137]
	v_mfma_f32_16x16x32_bf16 v[130:133], v[170:173], v[200:203], v[130:133]
	v_mfma_f32_16x16x32_bf16 v[118:121], v[162:165], v[208:211], v[118:121]
	v_mfma_f32_16x16x32_bf16 v[114:117], v[170:173], v[208:211], v[114:117]
	v_mfma_f32_16x16x32_bf16 v[102:105], v[162:165], v[216:219], v[102:105]
	v_mfma_f32_16x16x32_bf16 v[98:101], v[170:173], v[216:219], v[98:101]
	v_mfma_f32_16x16x32_bf16 v[86:89], v[162:165], v[232:235], v[86:89]
	s_barrier
; #define PG8_STAGE(bufoff, gbase, voff) do { _Pragma("unroll") for (int _i = 0; _i < 2; ++_i) \
;         __builtin_amdgcn_global_load_lds((const unsigned*)((const char*)(gbase) + (voff)[_i]), (PG8_LAS unsigned*)(lds + (bufoff) + ldsw + _i * 8192), 16, 0, 0); } while (0)
; #define PG8_LDA(dst, b, h) do { _Pragma("unroll") for (int m = 0; m < 4; ++m) _Pragma("unroll") for (int k = 0; k < 2; ++k) dst[m][k] = *(const PG8_LAS bf16x8*)(lds + PG8_SA(b, h) + aoff + m * 2048 + k * 1024); } while (0)
; #define PG8_MMA(ai, bj, At, Bt) do { __builtin_amdgcn_s_setprio(1); _Pragma("unroll") for (int m = 0; m < 4; ++m) _Pragma("unroll") for (int n = 0; n < 2; ++n) _Pragma("unroll") for (int k = 0; k < 2; ++k) \
;         acc[ai][bj][m][n] = __builtin_amdgcn_mfma_f32_16x16x32_bf16(Bt[n][k], At[m][k], acc[ai][bj][m][n], 0, 0, 0); __builtin_amdgcn_s_setprio(0); } while (0)
; #define PG8_WAIT_V(n) asm volatile("s_waitcnt vmcnt(" #n ")" ::: "memory")
; #define PG8_WAIT_L(n) asm volatile("s_waitcnt lgkmcnt(" #n ")" ::: "memory")
; #define PG8_BAR __builtin_amdgcn_s_barrier()
; #define PG8_SCHED __builtin_amdgcn_sched_barrier(0)
; template <class Epi, class Sched, bool ALIGN_EPI = false, bool SP2 = false>
; __device__ __forceinline__ void gemm_phase(PG8_LAS unsigned char* lds, const Gemm g, const Sched& S, const Epi& E, int tid_in) {
;     ...
;             PG8_LDA(At, 1, 1); PG8_STAGE(PG8_SB(1, 0), b3, voffB); PG8_STAGE(PG8_SB(1, 1), b3 + hstep, voffB); PG8_STAGE(PG8_SA(1, 0), a3, voffA);
;             PG8_WAIT_V(8); PG8_WAIT_L(0); PG8_BAR; PG8_MMA(1, 0, At, B0); PG8_MMA(1, 1, At, B1); PG8_BAR; PG8_SCHED;
;     ...
;         if constexpr (ALIGN_EPI) { if (wr == 0) PG8_BAR; }
	v_mfma_f32_16x16x32_bf16 v[82:85], v[170:173], v[232:235], v[82:85]
	s_setprio 0
	s_mov_b32 m0, s67
	v_lshl_add_u64 v[174:175], v[174:175], 0, s[48:49]
	s_add_u32 s58, s86, 0x40080
	ds_read_b128 v[182:185], v177 offset:49152
	ds_read_b128 v[200:203], v177 offset:50176
	ds_read_b128 v[204:207], v177 offset:51200
	ds_read_b128 v[208:211], v177 offset:52224
	ds_read_b128 v[212:215], v177 offset:53248
	ds_read_b128 v[216:219], v177 offset:54272
	ds_read_b128 v[226:229], v177 offset:55296
	ds_read_b128 v[232:235], v177 offset:56320
	global_load_lds_dwordx4 v[174:175], off
	v_lshl_add_u64 v[174:175], v[178:179], 0, s[48:49]
	s_mov_b32 m0, s91
	s_addc_u32 s59, s87, 0
	global_load_lds_dwordx4 v[174:175], off
	v_lshl_add_u64 v[174:175], s[58:59], 0, v[148:149]
	s_mov_b32 m0, s75
	s_nop 0
	global_load_lds_dwordx4 v[174:175], off
	v_lshl_add_u64 v[174:175], s[58:59], 0, v[152:153]
	s_mov_b32 m0, s74
	s_nop 0
	global_load_lds_dwordx4 v[174:175], off
	v_lshl_add_u64 v[174:175], v[180:181], 0, s[48:49]
	s_mov_b32 m0, s53
	s_nop 0
	global_load_lds_dwordx4 v[174:175], off
	v_lshl_add_u64 v[174:175], v[236:237], 0, s[48:49]
	s_mov_b32 m0, s66
	s_nop 0
	global_load_lds_dwordx4 v[174:175], off
	s_waitcnt vmcnt(8)
	s_waitcnt lgkmcnt(0)
	s_barrier
	s_setprio 1
	s_waitcnt lgkmcnt(0)
	v_mfma_f32_16x16x32_bf16 v[76:79], v[48:51], v[182:185], v[76:79]
	v_mfma_f32_16x16x32_bf16 v[72:75], v[64:67], v[182:185], v[72:75]
	v_mfma_f32_16x16x32_bf16 v[60:63], v[48:51], v[204:207], v[60:63]
	v_mfma_f32_16x16x32_bf16 v[56:59], v[64:67], v[204:207], v[56:59]
	v_mfma_f32_16x16x32_bf16 v[28:31], v[48:51], v[212:215], v[28:31]
	v_mfma_f32_16x16x32_bf16 v[24:27], v[64:67], v[212:215], v[24:27]
	v_mfma_f32_16x16x32_bf16 v[12:15], v[48:51], v[226:229], v[12:15]
	v_mfma_f32_16x16x32_bf16 v[8:11], v[64:67], v[226:229], v[8:11]
	v_mfma_f32_16x16x32_bf16 v[76:79], v[52:55], v[200:203], v[76:79]
	v_mfma_f32_16x16x32_bf16 v[72:75], v[68:71], v[200:203], v[72:75]
	v_mfma_f32_16x16x32_bf16 v[60:63], v[52:55], v[208:211], v[60:63]
	v_mfma_f32_16x16x32_bf16 v[56:59], v[68:71], v[208:211], v[56:59]
	v_mfma_f32_16x16x32_bf16 v[28:31], v[52:55], v[216:219], v[28:31]
	v_mfma_f32_16x16x32_bf16 v[24:27], v[68:71], v[216:219], v[24:27]
	v_mfma_f32_16x16x32_bf16 v[12:15], v[52:55], v[232:235], v[12:15]
	v_mfma_f32_16x16x32_bf16 v[8:11], v[68:71], v[232:235], v[8:11]
	s_setprio 0
	s_setprio 1
	v_mfma_f32_16x16x32_bf16 v[32:35], v[158:161], v[182:185], v[32:35]
	v_mfma_f32_16x16x32_bf16 v[68:71], v[162:165], v[200:203], v[32:35]
	v_mfma_f32_16x16x32_bf16 v[32:35], v[166:169], v[182:185], v[36:39]
	v_mfma_f32_16x16x32_bf16 v[64:67], v[170:173], v[200:203], v[32:35]
	v_mfma_f32_16x16x32_bf16 v[32:35], v[158:161], v[204:207], v[44:47]
	v_mfma_f32_16x16x32_bf16 v[52:55], v[162:165], v[208:211], v[32:35]
	v_mfma_f32_16x16x32_bf16 v[32:35], v[166:169], v[204:207], v[40:43]
	v_mfma_f32_16x16x32_bf16 v[20:23], v[158:161], v[212:215], v[20:23]
	v_mfma_f32_16x16x32_bf16 v[16:19], v[166:169], v[212:215], v[16:19]
	v_mfma_f32_16x16x32_bf16 v[4:7], v[158:161], v[226:229], v[4:7]
	v_mfma_f32_16x16x32_bf16 v[0:3], v[166:169], v[226:229], v[0:3]
	v_mfma_f32_16x16x32_bf16 v[40:43], v[170:173], v[208:211], v[32:35]
	v_mfma_f32_16x16x32_bf16 v[20:23], v[162:165], v[216:219], v[20:23]
	v_mfma_f32_16x16x32_bf16 v[16:19], v[170:173], v[216:219], v[16:19]
	v_mfma_f32_16x16x32_bf16 v[4:7], v[162:165], v[232:235], v[4:7]
	s_barrier
	v_mfma_f32_16x16x32_bf16 v[0:3], v[170:173], v[232:235], v[0:3]
	s_setprio 0
	s_add_i32 s27, s27, 2
	s_add_u32 s84, s84, 0x100
	s_addc_u32 s85, s85, 0
	s_add_u32 s25, s25, 0x100
	s_addc_u32 s26, s26, 0
	s_cmp_gt_u32 s27, 13
	s_cbranch_scc0 .LBB0_158
	v_readlane_b32 s22, v254, 30
	v_readlane_b32 s23, v254, 31
	s_and_b64 vcc, exec, s[22:23]
	s_cbranch_vccz .LBB0_161
	s_barrier
	s_setprio 1

; #define PG8_STAGE(bufoff, gbase, voff) do { _Pragma("unroll") for (int _i = 0; _i < 2; ++_i) \
;         __builtin_amdgcn_global_load_lds((const unsigned*)((const char*)(gbase) + (voff)[_i]), (PG8_LAS unsigned*)(lds + (bufoff) + ldsw + _i * 8192), 16, 0, 0); } while (0)
; #define PG8_LDA(dst, b, h) do { _Pragma("unroll") for (int m = 0; m < 4; ++m) _Pragma("unroll") for (int k = 0; k < 2; ++k) dst[m][k] = *(const PG8_LAS bf16x8*)(lds + PG8_SA(b, h) + aoff + m * 2048 + k * 1024); } while (0)
; #define PG8_LDB(dst, b, h) do { _Pragma("unroll") for (int n = 0; n < 2; ++n) _Pragma("unroll") for (int k = 0; k < 2; ++k) dst[n][k] = *(const PG8_LAS bf16x8*)(lds + PG8_SB(b, h) + boff + n * 2048 + k * 1024); } while (0)
; #define PG8_MMA(ai, bj, At, Bt) do { __builtin_amdgcn_s_setprio(1); _Pragma("unroll") for (int m = 0; m < 4; ++m) _Pragma("unroll") for (int n = 0; n < 2; ++n) _Pragma("unroll") for (int k = 0; k < 2; ++k) \
;         acc[ai][bj][m][n] = __builtin_amdgcn_mfma_f32_16x16x32_bf16(Bt[n][k], At[m][k], acc[ai][bj][m][n], 0, 0, 0); __builtin_amdgcn_s_setprio(0); } while (0)
; #define PG8_WAIT_V(n) asm volatile("s_waitcnt vmcnt(" #n ")" ::: "memory")
; #define PG8_WAIT_L(n) asm volatile("s_waitcnt lgkmcnt(" #n ")" ::: "memory")
; #define PG8_BAR __builtin_amdgcn_s_barrier()
; #define PG8_SCHED __builtin_amdgcn_sched_barrier(0)
; template <class Epi, class Sched, bool ALIGN_EPI = false, bool SP2 = false>
; __device__ __forceinline__ void gemm_phase(PG8_LAS unsigned char* lds, const Gemm g, const Sched& S, const Epi& E, int tid_in) {
;     ...
;             PG8_LDB(B0, 0, 0); PG8_LDB(B1, 0, 1); PG8_SCHED; PG8_LDA(At, 0, 0); PG8_STAGE(PG8_SA(1, 1), a1 + hstep, voffA);
;             PG8_WAIT_V(8); PG8_WAIT_L(0); PG8_BAR; PG8_MMA(0, 0, At, B0); PG8_MMA(0, 1, At, B1); PG8_BAR; PG8_SCHED;
;             PG8_LDA(At, 0, 1); PG8_STAGE(PG8_SB(0, 0), b2, voffB); PG8_STAGE(PG8_SB(0, 1), b2 + hstep, voffB); PG8_STAGE(PG8_SA(0, 0), a2, voffA);
;             PG8_WAIT_V(8); PG8_WAIT_L(0); PG8_BAR; PG8_MMA(1, 0, At, B0); PG8_MMA(1, 1, At, B1); PG8_BAR; PG8_SCHED;
.LBB0_440:
	v_or_b32_e32 v130, 0x10000, v248
	v_add_u32_e32 v134, 0x10400, v248
	v_add_u32_e32 v138, 0x10800, v248
	v_add_u32_e32 v142, 0x10c00, v248
	v_or_b32_e32 v146, 0x14000, v248
	v_add_u32_e32 v150, 0x14400, v248
	v_add_u32_e32 v154, 0x14800, v248
	v_add_u32_e32 v158, 0x14c00, v248
	ds_read_b128 v[130:133], v130
	ds_read_b128 v[134:137], v134
	ds_read_b128 v[138:141], v138
	ds_read_b128 v[142:145], v142
	ds_read_b128 v[146:149], v146
	ds_read_b128 v[150:153], v150
	ds_read_b128 v[154:157], v154
	ds_read_b128 v[158:161], v158
	s_add_u32 s80, s78, 0xfffc0080
	s_addc_u32 s81, s79, -1
	s_cmp_eq_u32 s87, 12
	s_cselect_b32 s83, s71, s81
	s_cselect_b32 s82, s77, s80
	s_cselect_b32 s81, s67, s86
	s_cselect_b32 s80, s84, s85
	v_lshl_add_u64 v[178:179], s[78:79], 0, v[202:203]
	s_add_i32 m0, s57, 0xc000
	ds_read_b128 v[162:165], v247
	ds_read_b128 v[166:169], v247 offset:1024
	ds_read_b128 v[170:173], v247 offset:2048
	ds_read_b128 v[174:177], v247 offset:3072
	ds_read_b128 v[182:185], v247 offset:4096
	ds_read_b128 v[212:215], v247 offset:5120
	ds_read_b128 v[226:229], v247 offset:6144
	ds_read_b128 v[232:235], v247 offset:7168
	global_load_lds_dwordx4 v[178:179], off
	v_lshl_add_u64 v[178:179], s[78:79], 0, v[204:205]
	s_add_i32 m0, s57, 0xe000
	s_nop 0
	global_load_lds_dwordx4 v[178:179], off
	s_waitcnt vmcnt(8)
	s_waitcnt lgkmcnt(0)
	s_barrier
	s_setprio 1
	s_waitcnt lgkmcnt(0)
	v_mfma_f32_16x16x32_bf16 v[126:129], v[130:133], v[162:165], v[126:129]
	v_mfma_f32_16x16x32_bf16 v[122:125], v[138:141], v[162:165], v[122:125]
	v_mfma_f32_16x16x32_bf16 v[114:117], v[130:133], v[170:173], v[114:117]
	v_mfma_f32_16x16x32_bf16 v[106:109], v[138:141], v[170:173], v[106:109]
	v_mfma_f32_16x16x32_bf16 v[98:101], v[130:133], v[182:185], v[98:101]
	v_mfma_f32_16x16x32_bf16 v[90:93], v[138:141], v[182:185], v[90:93]
	v_mfma_f32_16x16x32_bf16 v[76:79], v[130:133], v[226:229], v[76:79]
	v_mfma_f32_16x16x32_bf16 v[72:75], v[138:141], v[226:229], v[72:75]
	v_mfma_f32_16x16x32_bf16 v[126:129], v[134:137], v[166:169], v[126:129]
	v_mfma_f32_16x16x32_bf16 v[122:125], v[142:145], v[166:169], v[122:125]
	v_mfma_f32_16x16x32_bf16 v[114:117], v[134:137], v[174:177], v[114:117]
	v_mfma_f32_16x16x32_bf16 v[106:109], v[142:145], v[174:177], v[106:109]
	v_mfma_f32_16x16x32_bf16 v[98:101], v[134:137], v[212:215], v[98:101]
	v_mfma_f32_16x16x32_bf16 v[90:93], v[142:145], v[212:215], v[90:93]
	v_mfma_f32_16x16x32_bf16 v[76:79], v[134:137], v[232:235], v[76:79]
	v_mfma_f32_16x16x32_bf16 v[72:75], v[142:145], v[232:235], v[72:75]
	s_setprio 0
	s_setprio 1
	v_mfma_f32_16x16x32_bf16 v[118:121], v[146:149], v[162:165], v[118:121]
	v_mfma_f32_16x16x32_bf16 v[110:113], v[154:157], v[162:165], v[110:113]
	v_mfma_f32_16x16x32_bf16 v[102:105], v[146:149], v[170:173], v[102:105]
	v_mfma_f32_16x16x32_bf16 v[94:97], v[154:157], v[170:173], v[94:97]
	v_mfma_f32_16x16x32_bf16 v[86:89], v[146:149], v[182:185], v[86:89]
	v_mfma_f32_16x16x32_bf16 v[82:85], v[154:157], v[182:185], v[82:85]
	v_mfma_f32_16x16x32_bf16 v[68:71], v[146:149], v[226:229], v[68:71]
	v_mfma_f32_16x16x32_bf16 v[64:67], v[154:157], v[226:229], v[64:67]
	v_mfma_f32_16x16x32_bf16 v[118:121], v[150:153], v[166:169], v[118:121]
	v_mfma_f32_16x16x32_bf16 v[110:113], v[158:161], v[166:169], v[110:113]
	v_mfma_f32_16x16x32_bf16 v[102:105], v[150:153], v[174:177], v[102:105]
	v_mfma_f32_16x16x32_bf16 v[94:97], v[158:161], v[174:177], v[94:97]
	v_mfma_f32_16x16x32_bf16 v[86:89], v[150:153], v[212:215], v[86:89]
	v_mfma_f32_16x16x32_bf16 v[82:85], v[158:161], v[212:215], v[82:85]
	v_mfma_f32_16x16x32_bf16 v[68:71], v[150:153], v[232:235], v[68:71]
	s_barrier
	v_mfma_f32_16x16x32_bf16 v[64:67], v[158:161], v[232:235], v[64:67]
	s_setprio 0
	s_mov_b32 m0, s20
	v_lshl_add_u64 v[178:179], s[80:81], 0, v[198:199]
	s_add_u32 s88, s80, 0x40000
	ds_read_b128 v[162:165], v247 offset:16384
	ds_read_b128 v[166:169], v247 offset:17408
	ds_read_b128 v[170:173], v247 offset:18432
	ds_read_b128 v[174:177], v247 offset:19456
	ds_read_b128 v[182:185], v247 offset:20480
	ds_read_b128 v[212:215], v247 offset:21504
	ds_read_b128 v[226:229], v247 offset:22528
	ds_read_b128 v[232:235], v247 offset:23552
	global_load_lds_dwordx4 v[178:179], off
	v_lshl_add_u64 v[180:181], s[80:81], 0, v[194:195]
	s_mov_b32 m0, s21
	s_addc_u32 s89, s81, 0
	global_load_lds_dwordx4 v[180:181], off
	v_lshl_add_u64 v[208:209], s[88:89], 0, v[198:199]
	s_mov_b32 m0, s22
	v_lshl_add_u64 v[218:219], s[82:83], 0, v[196:197]
	global_load_lds_dwordx4 v[208:209], off
	v_lshl_add_u64 v[208:209], s[88:89], 0, v[194:195]
	s_mov_b32 m0, s23
	s_nop 0
	global_load_lds_dwordx4 v[208:209], off
	v_lshl_add_u64 v[208:209], s[82:83], 0, v[200:201]
	s_mov_b32 m0, s57
	s_nop 0
	global_load_lds_dwordx4 v[208:209], off
	s_mov_b32 m0, s24
	s_nop 0
	global_load_lds_dwordx4 v[218:219], off
	s_waitcnt vmcnt(8)
	s_waitcnt lgkmcnt(0)
	s_barrier
; #define PG8_STAGE(bufoff, gbase, voff) do { _Pragma("unroll") for (int _i = 0; _i < 2; ++_i) \
;         __builtin_amdgcn_global_load_lds((const unsigned*)((const char*)(gbase) + (voff)[_i]), (PG8_LAS unsigned*)(lds + (bufoff) + ldsw + _i * 8192), 16, 0, 0); } while (0)
; #define PG8_LDA(dst, b, h) do { _Pragma("unroll") for (int m = 0; m < 4; ++m) _Pragma("unroll") for (int k = 0; k < 2; ++k) dst[m][k] = *(const PG8_LAS bf16x8*)(lds + PG8_SA(b, h) + aoff + m * 2048 + k * 1024); } while (0)
; #define PG8_LDB(dst, b, h) do { _Pragma("unroll") for (int n = 0; n < 2; ++n) _Pragma("unroll") for (int k = 0; k < 2; ++k) dst[n][k] = *(const PG8_LAS bf16x8*)(lds + PG8_SB(b, h) + boff + n * 2048 + k * 1024); } while (0)
; #define PG8_MMA(ai, bj, At, Bt) do { __builtin_amdgcn_s_setprio(1); _Pragma("unroll") for (int m = 0; m < 4; ++m) _Pragma("unroll") for (int n = 0; n < 2; ++n) _Pragma("unroll") for (int k = 0; k < 2; ++k) \
;         acc[ai][bj][m][n] = __builtin_amdgcn_mfma_f32_16x16x32_bf16(Bt[n][k], At[m][k], acc[ai][bj][m][n], 0, 0, 0); __builtin_amdgcn_s_setprio(0); } while (0)
; #define PG8_WAIT_V(n) asm volatile("s_waitcnt vmcnt(" #n ")" ::: "memory")
; #define PG8_WAIT_L(n) asm volatile("s_waitcnt lgkmcnt(" #n ")" ::: "memory")
; #define PG8_BAR __builtin_amdgcn_s_barrier()
; #define PG8_SCHED __builtin_amdgcn_sched_barrier(0)
; template <class Epi, class Sched, bool ALIGN_EPI = false, bool SP2 = false>
; __device__ __forceinline__ void gemm_phase(PG8_LAS unsigned char* lds, const Gemm g, const Sched& S, const Epi& E, int tid_in) {
;     ...
;             PG8_WAIT_V(8); PG8_WAIT_L(0); PG8_BAR; PG8_MMA(1, 0, At, B0); PG8_MMA(1, 1, At, B1); PG8_BAR; PG8_SCHED;
;             PG8_LDB(B0, 1, 0); PG8_LDB(B1, 1, 1); PG8_SCHED; PG8_LDA(At, 1, 0); PG8_STAGE(PG8_SA(0, 1), a2 + hstep, voffA);
;             PG8_WAIT_V(8); PG8_WAIT_L(0); PG8_BAR; PG8_MMA(0, 0, At, B0); PG8_MMA(0, 1, At, B1); PG8_BAR; PG8_SCHED;
	s_setprio 1
	s_waitcnt lgkmcnt(0)
	v_mfma_f32_16x16x32_bf16 v[60:63], v[130:133], v[162:165], v[60:63]
	v_mfma_f32_16x16x32_bf16 v[56:59], v[138:141], v[162:165], v[56:59]
	v_mfma_f32_16x16x32_bf16 v[44:47], v[130:133], v[170:173], v[44:47]
	v_mfma_f32_16x16x32_bf16 v[40:43], v[138:141], v[170:173], v[40:43]
	v_mfma_f32_16x16x32_bf16 v[28:31], v[130:133], v[182:185], v[28:31]
	v_mfma_f32_16x16x32_bf16 v[24:27], v[138:141], v[182:185], v[24:27]
	v_mfma_f32_16x16x32_bf16 v[12:15], v[130:133], v[226:229], v[12:15]
	v_mfma_f32_16x16x32_bf16 v[8:11], v[138:141], v[226:229], v[8:11]
	v_mfma_f32_16x16x32_bf16 v[60:63], v[134:137], v[166:169], v[60:63]
	v_mfma_f32_16x16x32_bf16 v[56:59], v[142:145], v[166:169], v[56:59]
	v_mfma_f32_16x16x32_bf16 v[44:47], v[134:137], v[174:177], v[44:47]
	v_mfma_f32_16x16x32_bf16 v[40:43], v[142:145], v[174:177], v[40:43]
	v_mfma_f32_16x16x32_bf16 v[28:31], v[134:137], v[212:215], v[28:31]
	v_mfma_f32_16x16x32_bf16 v[24:27], v[142:145], v[212:215], v[24:27]
	v_mfma_f32_16x16x32_bf16 v[12:15], v[134:137], v[232:235], v[12:15]
	v_mfma_f32_16x16x32_bf16 v[8:11], v[142:145], v[232:235], v[8:11]
	s_setprio 0
	s_setprio 1
	v_mfma_f32_16x16x32_bf16 v[52:55], v[146:149], v[162:165], v[52:55]
	v_mfma_f32_16x16x32_bf16 v[48:51], v[154:157], v[162:165], v[48:51]
	v_mfma_f32_16x16x32_bf16 v[36:39], v[146:149], v[170:173], v[36:39]
	v_mfma_f32_16x16x32_bf16 v[32:35], v[154:157], v[170:173], v[32:35]
	v_mfma_f32_16x16x32_bf16 v[20:23], v[146:149], v[182:185], v[20:23]
	v_mfma_f32_16x16x32_bf16 v[16:19], v[154:157], v[182:185], v[16:19]
	v_mfma_f32_16x16x32_bf16 v[4:7], v[146:149], v[226:229], v[4:7]
	v_mfma_f32_16x16x32_bf16 v[0:3], v[154:157], v[226:229], v[0:3]
	v_mfma_f32_16x16x32_bf16 v[52:55], v[150:153], v[166:169], v[52:55]
	v_mfma_f32_16x16x32_bf16 v[48:51], v[158:161], v[166:169], v[48:51]
	v_mfma_f32_16x16x32_bf16 v[36:39], v[150:153], v[174:177], v[36:39]
	v_mfma_f32_16x16x32_bf16 v[32:35], v[158:161], v[174:177], v[32:35]
	v_mfma_f32_16x16x32_bf16 v[20:23], v[150:153], v[212:215], v[20:23]
	v_mfma_f32_16x16x32_bf16 v[16:19], v[158:161], v[212:215], v[16:19]
	v_mfma_f32_16x16x32_bf16 v[4:7], v[150:153], v[232:235], v[4:7]
	s_barrier
	v_mfma_f32_16x16x32_bf16 v[0:3], v[158:161], v[232:235], v[0:3]
	s_setprio 0
	v_or_b32_e32 v130, 0x18000, v248
	v_add_u32_e32 v134, 0x18400, v248
	v_add_u32_e32 v138, 0x18800, v248
	v_add_u32_e32 v142, 0x18c00, v248
	v_or_b32_e32 v146, 0x1c000, v248
	v_add_u32_e32 v150, 0x1c400, v248
	v_add_u32_e32 v154, 0x1c800, v248
	v_add_u32_e32 v158, 0x1cc00, v248
	ds_read_b128 v[130:133], v130
	ds_read_b128 v[134:137], v134
	ds_read_b128 v[138:141], v138
	ds_read_b128 v[142:145], v142
	ds_read_b128 v[146:149], v146
	ds_read_b128 v[150:153], v150
	ds_read_b128 v[154:157], v154
	ds_read_b128 v[158:161], v158
	s_add_u32 s82, s82, 0x40000
	s_addc_u32 s83, s83, 0
	s_mov_b32 m0, s25
	v_lshl_add_u64 v[236:237], s[82:83], 0, v[200:201]
	ds_read_b128 v[162:165], v247 offset:32768
	ds_read_b128 v[166:169], v247 offset:33792
	ds_read_b128 v[170:173], v247 offset:34816
	ds_read_b128 v[174:177], v247 offset:35840
	ds_read_b128 v[182:185], v247 offset:36864
	ds_read_b128 v[212:215], v247 offset:37888
	ds_read_b128 v[226:229], v247 offset:38912
	ds_read_b128 v[232:235], v247 offset:39936
	global_load_lds_dwordx4 v[236:237], off
	v_lshl_add_u64 v[236:237], s[82:83], 0, v[196:197]
	s_mov_b32 m0, s26
	s_nop 0
	global_load_lds_dwordx4 v[236:237], off
	s_waitcnt vmcnt(8)
	s_waitcnt lgkmcnt(0)
	s_barrier
	s_setprio 1
	s_waitcnt lgkmcnt(0)
	v_mfma_f32_16x16x32_bf16 v[126:129], v[130:133], v[162:165], v[126:129]
	v_mfma_f32_16x16x32_bf16 v[122:125], v[138:141], v[162:165], v[122:125]
	v_mfma_f32_16x16x32_bf16 v[114:117], v[130:133], v[170:173], v[114:117]
	v_mfma_f32_16x16x32_bf16 v[106:109], v[138:141], v[170:173], v[106:109]
	v_mfma_f32_16x16x32_bf16 v[98:101], v[130:133], v[182:185], v[98:101]
	v_mfma_f32_16x16x32_bf16 v[90:93], v[138:141], v[182:185], v[90:93]
	v_mfma_f32_16x16x32_bf16 v[76:79], v[130:133], v[226:229], v[76:79]
	v_mfma_f32_16x16x32_bf16 v[72:75], v[138:141], v[226:229], v[72:75]
	v_mfma_f32_16x16x32_bf16 v[126:129], v[134:137], v[166:169], v[126:129]
	v_mfma_f32_16x16x32_bf16 v[122:125], v[142:145], v[166:169], v[122:125]
	v_mfma_f32_16x16x32_bf16 v[114:117], v[134:137], v[174:177], v[114:117]
	v_mfma_f32_16x16x32_bf16 v[106:109], v[142:145], v[174:177], v[106:109]
	v_mfma_f32_16x16x32_bf16 v[98:101], v[134:137], v[212:215], v[98:101]
	v_mfma_f32_16x16x32_bf16 v[90:93], v[142:145], v[212:215], v[90:93]
	v_mfma_f32_16x16x32_bf16 v[76:79], v[134:137], v[232:235], v[76:79]
	v_mfma_f32_16x16x32_bf16 v[72:75], v[142:145], v[232:235], v[72:75]
	s_setprio 0
	s_setprio 1
	v_mfma_f32_16x16x32_bf16 v[118:121], v[146:149], v[162:165], v[118:121]
	v_mfma_f32_16x16x32_bf16 v[110:113], v[154:157], v[162:165], v[110:113]
	v_mfma_f32_16x16x32_bf16 v[102:105], v[146:149], v[170:173], v[102:105]
	v_mfma_f32_16x16x32_bf16 v[94:97], v[154:157], v[170:173], v[94:97]
	v_mfma_f32_16x16x32_bf16 v[86:89], v[146:149], v[182:185], v[86:89]
	v_mfma_f32_16x16x32_bf16 v[82:85], v[154:157], v[182:185], v[82:85]
	v_mfma_f32_16x16x32_bf16 v[68:71], v[146:149], v[226:229], v[68:71]
	v_mfma_f32_16x16x32_bf16 v[64:67], v[154:157], v[226:229], v[64:67]
	v_mfma_f32_16x16x32_bf16 v[118:121], v[150:153], v[166:169], v[118:121]
	v_mfma_f32_16x16x32_bf16 v[110:113], v[158:161], v[166:169], v[110:113]
	v_mfma_f32_16x16x32_bf16 v[102:105], v[150:153], v[174:177], v[102:105]
	v_mfma_f32_16x16x32_bf16 v[94:97], v[158:161], v[174:177], v[94:97]
	v_mfma_f32_16x16x32_bf16 v[86:89], v[150:153], v[212:215], v[86:89]
	v_mfma_f32_16x16x32_bf16 v[82:85], v[158:161], v[212:215], v[82:85]
	v_mfma_f32_16x16x32_bf16 v[68:71], v[150:153], v[232:235], v[68:71]
	s_barrier
; #define PG8_STAGE(bufoff, gbase, voff) do { _Pragma("unroll") for (int _i = 0; _i < 2; ++_i) \
;         __builtin_amdgcn_global_load_lds((const unsigned*)((const char*)(gbase) + (voff)[_i]), (PG8_LAS unsigned*)(lds + (bufoff) + ldsw + _i * 8192), 16, 0, 0); } while (0)
; #define PG8_LDA(dst, b, h) do { _Pragma("unroll") for (int m = 0; m < 4; ++m) _Pragma("unroll") for (int k = 0; k < 2; ++k) dst[m][k] = *(const PG8_LAS bf16x8*)(lds + PG8_SA(b, h) + aoff + m * 2048 + k * 1024); } while (0)
; #define PG8_MMA(ai, bj, At, Bt) do { __builtin_amdgcn_s_setprio(1); _Pragma("unroll") for (int m = 0; m < 4; ++m) _Pragma("unroll") for (int n = 0; n < 2; ++n) _Pragma("unroll") for (int k = 0; k < 2; ++k) \
;         acc[ai][bj][m][n] = __builtin_amdgcn_mfma_f32_16x16x32_bf16(Bt[n][k], At[m][k], acc[ai][bj][m][n], 0, 0, 0); __builtin_amdgcn_s_setprio(0); } while (0)
; #define PG8_WAIT_V(n) asm volatile("s_waitcnt vmcnt(" #n ")" ::: "memory")
; #define PG8_WAIT_L(n) asm volatile("s_waitcnt lgkmcnt(" #n ")" ::: "memory")
; #define PG8_BAR __builtin_amdgcn_s_barrier()
; #define PG8_SCHED __builtin_amdgcn_sched_barrier(0)
; template <class Epi, class Sched, bool ALIGN_EPI = false, bool SP2 = false>
; __device__ __forceinline__ void gemm_phase(PG8_LAS unsigned char* lds, const Gemm g, const Sched& S, const Epi& E, int tid_in) {
;     ...
;             PG8_LDA(At, 1, 1); PG8_STAGE(PG8_SB(1, 0), b3, voffB); PG8_STAGE(PG8_SB(1, 1), b3 + hstep, voffB); PG8_STAGE(PG8_SA(1, 0), a3, voffA);
;             PG8_WAIT_V(8); PG8_WAIT_L(0); PG8_BAR; PG8_MMA(1, 0, At, B0); PG8_MMA(1, 1, At, B1); PG8_BAR; PG8_SCHED;
;     ...
;         if constexpr (ALIGN_EPI) { if (wr == 0) PG8_BAR; }
	v_mfma_f32_16x16x32_bf16 v[64:67], v[158:161], v[232:235], v[64:67]
	s_setprio 0
	s_mov_b32 m0, s27
	v_lshl_add_u64 v[178:179], v[178:179], 0, s[48:49]
	s_add_u32 s80, s80, 0x40080
	ds_read_b128 v[162:165], v247 offset:49152
	ds_read_b128 v[166:169], v247 offset:50176
	ds_read_b128 v[170:173], v247 offset:51200
	ds_read_b128 v[174:177], v247 offset:52224
	ds_read_b128 v[182:185], v247 offset:53248
	ds_read_b128 v[212:215], v247 offset:54272
	ds_read_b128 v[226:229], v247 offset:55296
	ds_read_b128 v[232:235], v247 offset:56320
	global_load_lds_dwordx4 v[178:179], off
	v_lshl_add_u64 v[178:179], v[180:181], 0, s[48:49]
	s_mov_b32 m0, s58
	s_addc_u32 s81, s81, 0
	global_load_lds_dwordx4 v[178:179], off
	v_lshl_add_u64 v[178:179], s[80:81], 0, v[198:199]
	s_mov_b32 m0, s63
	s_nop 0
	global_load_lds_dwordx4 v[178:179], off
	v_lshl_add_u64 v[178:179], s[80:81], 0, v[194:195]
	s_mov_b32 m0, s64
	s_nop 0
	global_load_lds_dwordx4 v[178:179], off
	v_lshl_add_u64 v[178:179], v[208:209], 0, s[48:49]
	s_mov_b32 m0, s59
	s_nop 0
	global_load_lds_dwordx4 v[178:179], off
	v_lshl_add_u64 v[178:179], v[218:219], 0, s[48:49]
	s_mov_b32 m0, s62
	s_nop 0
	global_load_lds_dwordx4 v[178:179], off
	s_waitcnt vmcnt(8)
	s_waitcnt lgkmcnt(0)
	s_barrier
	s_setprio 1
	s_waitcnt lgkmcnt(0)
	v_mfma_f32_16x16x32_bf16 v[60:63], v[130:133], v[162:165], v[60:63]
	v_mfma_f32_16x16x32_bf16 v[56:59], v[138:141], v[162:165], v[56:59]
	v_mfma_f32_16x16x32_bf16 v[44:47], v[130:133], v[170:173], v[44:47]
	v_mfma_f32_16x16x32_bf16 v[40:43], v[138:141], v[170:173], v[40:43]
	v_mfma_f32_16x16x32_bf16 v[28:31], v[130:133], v[182:185], v[28:31]
	v_mfma_f32_16x16x32_bf16 v[24:27], v[138:141], v[182:185], v[24:27]
	v_mfma_f32_16x16x32_bf16 v[12:15], v[130:133], v[226:229], v[12:15]
	v_mfma_f32_16x16x32_bf16 v[8:11], v[138:141], v[226:229], v[8:11]
	v_mfma_f32_16x16x32_bf16 v[60:63], v[134:137], v[166:169], v[60:63]
	v_mfma_f32_16x16x32_bf16 v[56:59], v[142:145], v[166:169], v[56:59]
	v_mfma_f32_16x16x32_bf16 v[44:47], v[134:137], v[174:177], v[44:47]
	v_mfma_f32_16x16x32_bf16 v[40:43], v[142:145], v[174:177], v[40:43]
	v_mfma_f32_16x16x32_bf16 v[28:31], v[134:137], v[212:215], v[28:31]
	v_mfma_f32_16x16x32_bf16 v[24:27], v[142:145], v[212:215], v[24:27]
	v_mfma_f32_16x16x32_bf16 v[12:15], v[134:137], v[232:235], v[12:15]
	v_mfma_f32_16x16x32_bf16 v[8:11], v[142:145], v[232:235], v[8:11]
	s_setprio 0
	s_setprio 1
	v_mfma_f32_16x16x32_bf16 v[52:55], v[146:149], v[162:165], v[52:55]
	v_mfma_f32_16x16x32_bf16 v[48:51], v[154:157], v[162:165], v[48:51]
	v_mfma_f32_16x16x32_bf16 v[36:39], v[146:149], v[170:173], v[36:39]
	v_mfma_f32_16x16x32_bf16 v[32:35], v[154:157], v[170:173], v[32:35]
	v_mfma_f32_16x16x32_bf16 v[20:23], v[146:149], v[182:185], v[20:23]
	v_mfma_f32_16x16x32_bf16 v[16:19], v[154:157], v[182:185], v[16:19]
	v_mfma_f32_16x16x32_bf16 v[4:7], v[146:149], v[226:229], v[4:7]
	v_mfma_f32_16x16x32_bf16 v[0:3], v[154:157], v[226:229], v[0:3]
	v_mfma_f32_16x16x32_bf16 v[52:55], v[150:153], v[166:169], v[52:55]
	v_mfma_f32_16x16x32_bf16 v[48:51], v[158:161], v[166:169], v[48:51]
	v_mfma_f32_16x16x32_bf16 v[36:39], v[150:153], v[174:177], v[36:39]
	v_mfma_f32_16x16x32_bf16 v[32:35], v[158:161], v[174:177], v[32:35]
	v_mfma_f32_16x16x32_bf16 v[20:23], v[150:153], v[212:215], v[20:23]
	v_mfma_f32_16x16x32_bf16 v[16:19], v[158:161], v[212:215], v[16:19]
	v_mfma_f32_16x16x32_bf16 v[4:7], v[150:153], v[232:235], v[4:7]
	s_barrier
	v_mfma_f32_16x16x32_bf16 v[0:3], v[158:161], v[232:235], v[0:3]
	s_setprio 0
	s_add_i32 s87, s87, 2
	s_add_u32 s78, s78, 0x100
	s_addc_u32 s79, s79, 0
	s_add_u32 s85, s85, 0x100
	s_addc_u32 s86, s86, 0
	s_cmp_gt_u32 s87, 13
	s_cbranch_scc0 .LBB0_440
	v_mov_b32_e32 v239, 0x60
	v_mov_b32_e32 v236, 0xc0
	s_and_b64 vcc, exec, s[42:43]
	s_cbranch_vccz .LBB0_443
	s_barrier
	s_setprio 1

; #define PG8_STAGE(bufoff, gbase, voff) do { _Pragma("unroll") for (int _i = 0; _i < 2; ++_i) \
;         __builtin_amdgcn_global_load_lds((const unsigned*)((const char*)(gbase) + (voff)[_i]), (PG8_LAS unsigned*)(lds + (bufoff) + ldsw + _i * 8192), 16, 0, 0); } while (0)
; #define PG8_LDA(dst, b, h) do { _Pragma("unroll") for (int m = 0; m < 4; ++m) _Pragma("unroll") for (int k = 0; k < 2; ++k) dst[m][k] = *(const PG8_LAS bf16x8*)(lds + PG8_SA(b, h) + aoff + m * 2048 + k * 1024); } while (0)
; #define PG8_LDB(dst, b, h) do { _Pragma("unroll") for (int n = 0; n < 2; ++n) _Pragma("unroll") for (int k = 0; k < 2; ++k) dst[n][k] = *(const PG8_LAS bf16x8*)(lds + PG8_SB(b, h) + boff + n * 2048 + k * 1024); } while (0)
; #define PG8_MMA(ai, bj, At, Bt) do { __builtin_amdgcn_s_setprio(1); _Pragma("unroll") for (int m = 0; m < 4; ++m) _Pragma("unroll") for (int n = 0; n < 2; ++n) _Pragma("unroll") for (int k = 0; k < 2; ++k) \
;         acc[ai][bj][m][n] = __builtin_amdgcn_mfma_f32_16x16x32_bf16(Bt[n][k], At[m][k], acc[ai][bj][m][n], 0, 0, 0); __builtin_amdgcn_s_setprio(0); } while (0)
; #define PG8_WAIT_V(n) asm volatile("s_waitcnt vmcnt(" #n ")" ::: "memory")
; #define PG8_WAIT_L(n) asm volatile("s_waitcnt lgkmcnt(" #n ")" ::: "memory")
; #define PG8_BAR __builtin_amdgcn_s_barrier()
; #define PG8_SCHED __builtin_amdgcn_sched_barrier(0)
; template <class Epi, class Sched, bool ALIGN_EPI = false, bool SP2 = false>
; __device__ __forceinline__ void gemm_phase(PG8_LAS unsigned char* lds, const Gemm g, const Sched& S, const Epi& E, int tid_in) {
;     ...
;             PG8_LDB(B0, 0, 0); PG8_LDB(B1, 0, 1); PG8_SCHED; PG8_LDA(At, 0, 0); PG8_STAGE(PG8_SA(1, 1), a1 + hstep, voffA);
;             PG8_WAIT_V(8); PG8_WAIT_L(0); PG8_BAR; PG8_MMA(0, 0, At, B0); PG8_MMA(0, 1, At, B1); PG8_BAR; PG8_SCHED;
;             PG8_LDA(At, 0, 1); PG8_STAGE(PG8_SB(0, 0), b2, voffB); PG8_STAGE(PG8_SB(0, 1), b2 + hstep, voffB); PG8_STAGE(PG8_SA(0, 0), a2, voffA);
;             PG8_WAIT_V(8); PG8_WAIT_L(0); PG8_BAR; PG8_MMA(1, 0, At, B0); PG8_MMA(1, 1, At, B1); PG8_BAR; PG8_SCHED;
.LBB0_508:
	v_or_b32_e32 v40, 0x10000, v215
	v_add_u32_e32 v44, 0x10400, v215
	v_add_u32_e32 v52, 0x10800, v215
	v_add_u32_e32 v60, 0x10c00, v215
	v_or_b32_e32 v146, 0x14000, v215
	v_add_u32_e32 v150, 0x14400, v215
	v_add_u32_e32 v154, 0x14800, v215
	v_add_u32_e32 v158, 0x14c00, v215
	s_add_i32 s44, s42, 2
	ds_read_b128 v[40:43], v40
	ds_read_b128 v[44:47], v44
	ds_read_b128 v[52:55], v52
	ds_read_b128 v[60:63], v60
	ds_read_b128 v[146:149], v146
	ds_read_b128 v[150:153], v150
	ds_read_b128 v[154:157], v154
	ds_read_b128 v[158:161], v158
	s_add_u32 s45, s40, 0x80
	s_addc_u32 s43, s41, 0
	s_cmp_eq_u32 s94, s42
	s_cselect_b32 s42, s88, s45
	s_cselect_b32 s43, s89, s43
	s_cselect_b32 s93, s91, s27
	s_cselect_b32 s92, s90, s26
	v_lshl_add_u64 v[218:219], s[40:41], 0, v[174:175]
	s_add_i32 m0, s57, 0xc000
	ds_read_b128 v[194:197], v214
	ds_read_b128 v[198:201], v214 offset:1024
	ds_read_b128 v[202:205], v214 offset:2048
	ds_read_b128 v[206:209], v214 offset:3072
	ds_read_b128 v[210:213], v214 offset:4096
	ds_read_b128 v[226:229], v214 offset:5120
	ds_read_b128 v[232:235], v214 offset:6144
	ds_read_b128 v[182:185], v214 offset:7168
	global_load_lds_dwordx4 v[218:219], off
	v_lshl_add_u64 v[218:219], s[40:41], 0, v[176:177]
	s_add_i32 m0, s57, 0xe000
	s_nop 0
	global_load_lds_dwordx4 v[218:219], off
	s_waitcnt vmcnt(8)
	s_waitcnt lgkmcnt(0)
	s_barrier
	s_setprio 1
	s_waitcnt lgkmcnt(0)
	v_mfma_f32_16x16x32_bf16 v[142:145], v[40:43], v[194:197], v[142:145]
	v_mfma_f32_16x16x32_bf16 v[138:141], v[52:55], v[194:197], v[138:141]
	v_mfma_f32_16x16x32_bf16 v[126:129], v[40:43], v[202:205], v[126:129]
	v_mfma_f32_16x16x32_bf16 v[122:125], v[52:55], v[202:205], v[122:125]
	v_mfma_f32_16x16x32_bf16 v[110:113], v[40:43], v[210:213], v[110:113]
	v_mfma_f32_16x16x32_bf16 v[106:109], v[52:55], v[210:213], v[106:109]
	v_mfma_f32_16x16x32_bf16 v[94:97], v[40:43], v[232:235], v[94:97]
	v_mfma_f32_16x16x32_bf16 v[90:93], v[52:55], v[232:235], v[90:93]
	v_mfma_f32_16x16x32_bf16 v[142:145], v[44:47], v[198:201], v[142:145]
	v_mfma_f32_16x16x32_bf16 v[138:141], v[60:63], v[198:201], v[138:141]
	v_mfma_f32_16x16x32_bf16 v[126:129], v[44:47], v[206:209], v[126:129]
	v_mfma_f32_16x16x32_bf16 v[122:125], v[60:63], v[206:209], v[122:125]
	v_mfma_f32_16x16x32_bf16 v[110:113], v[44:47], v[226:229], v[110:113]
	v_mfma_f32_16x16x32_bf16 v[106:109], v[60:63], v[226:229], v[106:109]
	v_mfma_f32_16x16x32_bf16 v[94:97], v[44:47], v[182:185], v[94:97]
	v_mfma_f32_16x16x32_bf16 v[90:93], v[60:63], v[182:185], v[90:93]
	s_setprio 0
	s_setprio 1
	v_mfma_f32_16x16x32_bf16 v[134:137], v[146:149], v[194:197], v[134:137]
	v_mfma_f32_16x16x32_bf16 v[130:133], v[154:157], v[194:197], v[130:133]
	v_mfma_f32_16x16x32_bf16 v[118:121], v[146:149], v[202:205], v[118:121]
	v_mfma_f32_16x16x32_bf16 v[114:117], v[154:157], v[202:205], v[114:117]
	v_mfma_f32_16x16x32_bf16 v[102:105], v[146:149], v[210:213], v[102:105]
	v_mfma_f32_16x16x32_bf16 v[98:101], v[154:157], v[210:213], v[98:101]
	v_mfma_f32_16x16x32_bf16 v[86:89], v[146:149], v[232:235], v[86:89]
	v_mfma_f32_16x16x32_bf16 v[82:85], v[154:157], v[232:235], v[82:85]
	v_mfma_f32_16x16x32_bf16 v[134:137], v[150:153], v[198:201], v[134:137]
	v_mfma_f32_16x16x32_bf16 v[130:133], v[158:161], v[198:201], v[130:133]
	v_mfma_f32_16x16x32_bf16 v[118:121], v[150:153], v[206:209], v[118:121]
	v_mfma_f32_16x16x32_bf16 v[114:117], v[158:161], v[206:209], v[114:117]
	v_mfma_f32_16x16x32_bf16 v[102:105], v[150:153], v[226:229], v[102:105]
	v_mfma_f32_16x16x32_bf16 v[98:101], v[158:161], v[226:229], v[98:101]
	v_mfma_f32_16x16x32_bf16 v[86:89], v[150:153], v[182:185], v[86:89]
	s_barrier
	v_mfma_f32_16x16x32_bf16 v[82:85], v[158:161], v[182:185], v[82:85]
	s_setprio 0
	s_mov_b32 m0, s95
	v_lshl_add_u64 v[218:219], s[92:93], 0, v[164:165]
	v_lshl_add_u64 v[250:251], s[92:93], 0, v[168:169]
	s_add_u32 s92, s92, s70
	ds_read_b128 v[182:185], v214 offset:16384
	ds_read_b128 v[194:197], v214 offset:17408
	ds_read_b128 v[198:201], v214 offset:18432
	ds_read_b128 v[202:205], v214 offset:19456
	ds_read_b128 v[206:209], v214 offset:20480
	ds_read_b128 v[210:213], v214 offset:21504
	ds_read_b128 v[226:229], v214 offset:22528
	ds_read_b128 v[232:235], v214 offset:23552
	global_load_lds_dwordx4 v[218:219], off
	s_mov_b32 m0, s31
	s_addc_u32 s93, s93, 0
	global_load_lds_dwordx4 v[250:251], off
	v_lshl_add_u64 v[236:237], s[92:93], 0, v[164:165]
	s_mov_b32 m0, s68
	v_lshl_add_u64 v[238:239], s[92:93], 0, v[168:169]
	global_load_lds_dwordx4 v[236:237], off
	s_mov_b32 m0, s69
	v_lshl_add_u64 v[240:241], s[42:43], 0, v[162:163]
	global_load_lds_dwordx4 v[238:239], off
	s_mov_b32 m0, s57
	v_lshl_add_u64 v[178:179], s[42:43], 0, v[166:167]
	global_load_lds_dwordx4 v[240:241], off
	s_mov_b32 m0, s29
	s_nop 0
	global_load_lds_dwordx4 v[178:179], off
	s_waitcnt vmcnt(8)
	s_waitcnt lgkmcnt(0)
	s_barrier
; #define PG8_STAGE(bufoff, gbase, voff) do { _Pragma("unroll") for (int _i = 0; _i < 2; ++_i) \
;         __builtin_amdgcn_global_load_lds((const unsigned*)((const char*)(gbase) + (voff)[_i]), (PG8_LAS unsigned*)(lds + (bufoff) + ldsw + _i * 8192), 16, 0, 0); } while (0)
; #define PG8_LDA(dst, b, h) do { _Pragma("unroll") for (int m = 0; m < 4; ++m) _Pragma("unroll") for (int k = 0; k < 2; ++k) dst[m][k] = *(const PG8_LAS bf16x8*)(lds + PG8_SA(b, h) + aoff + m * 2048 + k * 1024); } while (0)
; #define PG8_LDB(dst, b, h) do { _Pragma("unroll") for (int n = 0; n < 2; ++n) _Pragma("unroll") for (int k = 0; k < 2; ++k) dst[n][k] = *(const PG8_LAS bf16x8*)(lds + PG8_SB(b, h) + boff + n * 2048 + k * 1024); } while (0)
; #define PG8_MMA(ai, bj, At, Bt) do { __builtin_amdgcn_s_setprio(1); _Pragma("unroll") for (int m = 0; m < 4; ++m) _Pragma("unroll") for (int n = 0; n < 2; ++n) _Pragma("unroll") for (int k = 0; k < 2; ++k) \
;         acc[ai][bj][m][n] = __builtin_amdgcn_mfma_f32_16x16x32_bf16(Bt[n][k], At[m][k], acc[ai][bj][m][n], 0, 0, 0); __builtin_amdgcn_s_setprio(0); } while (0)
; #define PG8_WAIT_V(n) asm volatile("s_waitcnt vmcnt(" #n ")" ::: "memory")
; #define PG8_WAIT_L(n) asm volatile("s_waitcnt lgkmcnt(" #n ")" ::: "memory")
; #define PG8_BAR __builtin_amdgcn_s_barrier()
; #define PG8_SCHED __builtin_amdgcn_sched_barrier(0)
; template <class Epi, class Sched, bool ALIGN_EPI = false, bool SP2 = false>
; __device__ __forceinline__ void gemm_phase(PG8_LAS unsigned char* lds, const Gemm g, const Sched& S, const Epi& E, int tid_in) {
;     ...
;             PG8_WAIT_V(8); PG8_WAIT_L(0); PG8_BAR; PG8_MMA(1, 0, At, B0); PG8_MMA(1, 1, At, B1); PG8_BAR; PG8_SCHED;
;             PG8_LDB(B0, 1, 0); PG8_LDB(B1, 1, 1); PG8_SCHED; PG8_LDA(At, 1, 0); PG8_STAGE(PG8_SA(0, 1), a2 + hstep, voffA);
;             PG8_WAIT_V(8); PG8_WAIT_L(0); PG8_BAR; PG8_MMA(0, 0, At, B0); PG8_MMA(0, 1, At, B1); PG8_BAR; PG8_SCHED;
	s_setprio 1
	s_waitcnt lgkmcnt(0)
	v_mfma_f32_16x16x32_bf16 v[76:79], v[40:43], v[182:185], v[76:79]
	v_mfma_f32_16x16x32_bf16 v[72:75], v[52:55], v[182:185], v[72:75]
	v_mfma_f32_16x16x32_bf16 v[56:59], v[40:43], v[198:201], v[56:59]
	v_mfma_f32_16x16x32_bf16 v[48:51], v[52:55], v[198:201], v[48:51]
	v_mfma_f32_16x16x32_bf16 v[28:31], v[40:43], v[206:209], v[28:31]
	v_mfma_f32_16x16x32_bf16 v[24:27], v[52:55], v[206:209], v[24:27]
	v_mfma_f32_16x16x32_bf16 v[12:15], v[40:43], v[226:229], v[12:15]
	v_mfma_f32_16x16x32_bf16 v[8:11], v[52:55], v[226:229], v[8:11]
	v_mfma_f32_16x16x32_bf16 v[76:79], v[44:47], v[194:197], v[76:79]
	v_mfma_f32_16x16x32_bf16 v[72:75], v[60:63], v[194:197], v[72:75]
	v_mfma_f32_16x16x32_bf16 v[56:59], v[44:47], v[202:205], v[56:59]
	v_mfma_f32_16x16x32_bf16 v[48:51], v[60:63], v[202:205], v[48:51]
	v_mfma_f32_16x16x32_bf16 v[28:31], v[44:47], v[210:213], v[28:31]
	v_mfma_f32_16x16x32_bf16 v[24:27], v[60:63], v[210:213], v[24:27]
	v_mfma_f32_16x16x32_bf16 v[12:15], v[44:47], v[232:235], v[12:15]
	v_mfma_f32_16x16x32_bf16 v[8:11], v[60:63], v[232:235], v[8:11]
	s_setprio 0
	s_setprio 1
	v_mfma_f32_16x16x32_bf16 v[36:39], v[146:149], v[198:201], v[36:39]
	v_mfma_f32_16x16x32_bf16 v[32:35], v[154:157], v[198:201], v[32:35]
	v_mfma_f32_16x16x32_bf16 v[20:23], v[146:149], v[206:209], v[20:23]
	v_mfma_f32_16x16x32_bf16 v[16:19], v[154:157], v[206:209], v[16:19]
	v_mfma_f32_16x16x32_bf16 v[4:7], v[146:149], v[226:229], v[4:7]
	v_mfma_f32_16x16x32_bf16 v[0:3], v[154:157], v[226:229], v[0:3]
	v_mfma_f32_16x16x32_bf16 v[40:43], v[146:149], v[182:185], v[68:71]
	v_mfma_f32_16x16x32_bf16 v[44:47], v[154:157], v[182:185], v[64:67]
	v_mfma_f32_16x16x32_bf16 v[36:39], v[150:153], v[202:205], v[36:39]
	v_mfma_f32_16x16x32_bf16 v[32:35], v[158:161], v[202:205], v[32:35]
	v_mfma_f32_16x16x32_bf16 v[20:23], v[150:153], v[210:213], v[20:23]
	v_mfma_f32_16x16x32_bf16 v[16:19], v[158:161], v[210:213], v[16:19]
	v_mfma_f32_16x16x32_bf16 v[4:7], v[150:153], v[232:235], v[4:7]
	v_mfma_f32_16x16x32_bf16 v[0:3], v[158:161], v[232:235], v[0:3]
	v_mfma_f32_16x16x32_bf16 v[40:43], v[150:153], v[194:197], v[40:43]
	s_barrier
	v_mfma_f32_16x16x32_bf16 v[44:47], v[158:161], v[194:197], v[44:47]
	s_setprio 0
	v_or_b32_e32 v52, 0x18000, v215
	v_add_u32_e32 v60, 0x18400, v215
	v_add_u32_e32 v64, 0x18800, v215
	v_add_u32_e32 v68, 0x18c00, v215
	v_or_b32_e32 v146, 0x1c000, v215
	v_add_u32_e32 v150, 0x1c400, v215
	v_add_u32_e32 v154, 0x1c800, v215
	v_add_u32_e32 v158, 0x1cc00, v215
	ds_read_b128 v[52:55], v52
	ds_read_b128 v[60:63], v60
	ds_read_b128 v[64:67], v64
	ds_read_b128 v[68:71], v68
	ds_read_b128 v[146:149], v146
	ds_read_b128 v[150:153], v150
	ds_read_b128 v[154:157], v154
	ds_read_b128 v[158:161], v158
	s_add_u32 s42, s42, s70
	s_addc_u32 s43, s43, 0
	s_mov_b32 m0, s58
	v_lshl_add_u64 v[180:181], s[42:43], 0, v[162:163]
	ds_read_b128 v[182:185], v214 offset:32768
	ds_read_b128 v[194:197], v214 offset:33792
	ds_read_b128 v[198:201], v214 offset:34816
	ds_read_b128 v[202:205], v214 offset:35840
	ds_read_b128 v[206:209], v214 offset:36864
	ds_read_b128 v[210:213], v214 offset:37888
	ds_read_b128 v[226:229], v214 offset:38912
	ds_read_b128 v[232:235], v214 offset:39936
	global_load_lds_dwordx4 v[180:181], off
	v_lshl_add_u64 v[180:181], s[42:43], 0, v[166:167]
	s_mov_b32 m0, s59
	s_nop 0
	global_load_lds_dwordx4 v[180:181], off
	s_waitcnt vmcnt(8)
	s_waitcnt lgkmcnt(0)
	s_barrier
	s_setprio 1
	s_waitcnt lgkmcnt(0)
	v_mfma_f32_16x16x32_bf16 v[142:145], v[52:55], v[182:185], v[142:145]
	v_mfma_f32_16x16x32_bf16 v[138:141], v[64:67], v[182:185], v[138:141]
	v_mfma_f32_16x16x32_bf16 v[126:129], v[52:55], v[198:201], v[126:129]
	v_mfma_f32_16x16x32_bf16 v[122:125], v[64:67], v[198:201], v[122:125]
	v_mfma_f32_16x16x32_bf16 v[110:113], v[52:55], v[206:209], v[110:113]
	v_mfma_f32_16x16x32_bf16 v[106:109], v[64:67], v[206:209], v[106:109]
	v_mfma_f32_16x16x32_bf16 v[94:97], v[52:55], v[226:229], v[94:97]
	v_mfma_f32_16x16x32_bf16 v[90:93], v[64:67], v[226:229], v[90:93]
	v_mfma_f32_16x16x32_bf16 v[142:145], v[60:63], v[194:197], v[142:145]
	v_mfma_f32_16x16x32_bf16 v[138:141], v[68:71], v[194:197], v[138:141]
	v_mfma_f32_16x16x32_bf16 v[126:129], v[60:63], v[202:205], v[126:129]
	v_mfma_f32_16x16x32_bf16 v[122:125], v[68:71], v[202:205], v[122:125]
	v_mfma_f32_16x16x32_bf16 v[110:113], v[60:63], v[210:213], v[110:113]
	v_mfma_f32_16x16x32_bf16 v[106:109], v[68:71], v[210:213], v[106:109]
	v_mfma_f32_16x16x32_bf16 v[94:97], v[60:63], v[232:235], v[94:97]
	v_mfma_f32_16x16x32_bf16 v[90:93], v[68:71], v[232:235], v[90:93]
	s_setprio 0
	s_setprio 1
	v_mfma_f32_16x16x32_bf16 v[134:137], v[146:149], v[182:185], v[134:137]
	v_mfma_f32_16x16x32_bf16 v[130:133], v[154:157], v[182:185], v[130:133]
	v_mfma_f32_16x16x32_bf16 v[118:121], v[146:149], v[198:201], v[118:121]
	v_mfma_f32_16x16x32_bf16 v[114:117], v[154:157], v[198:201], v[114:117]
	v_mfma_f32_16x16x32_bf16 v[102:105], v[146:149], v[206:209], v[102:105]
	v_mfma_f32_16x16x32_bf16 v[98:101], v[154:157], v[206:209], v[98:101]
	v_mfma_f32_16x16x32_bf16 v[86:89], v[146:149], v[226:229], v[86:89]
	v_mfma_f32_16x16x32_bf16 v[82:85], v[154:157], v[226:229], v[82:85]
	v_mfma_f32_16x16x32_bf16 v[134:137], v[150:153], v[194:197], v[134:137]
	v_mfma_f32_16x16x32_bf16 v[130:133], v[158:161], v[194:197], v[130:133]
	v_mfma_f32_16x16x32_bf16 v[118:121], v[150:153], v[202:205], v[118:121]
	v_mfma_f32_16x16x32_bf16 v[114:117], v[158:161], v[202:205], v[114:117]
	v_mfma_f32_16x16x32_bf16 v[102:105], v[150:153], v[210:213], v[102:105]
	v_mfma_f32_16x16x32_bf16 v[98:101], v[158:161], v[210:213], v[98:101]
	v_mfma_f32_16x16x32_bf16 v[86:89], v[150:153], v[232:235], v[86:89]
	s_barrier
; #define PG8_STAGE(bufoff, gbase, voff) do { _Pragma("unroll") for (int _i = 0; _i < 2; ++_i) \
;         __builtin_amdgcn_global_load_lds((const unsigned*)((const char*)(gbase) + (voff)[_i]), (PG8_LAS unsigned*)(lds + (bufoff) + ldsw + _i * 8192), 16, 0, 0); } while (0)
; #define PG8_LDA(dst, b, h) do { _Pragma("unroll") for (int m = 0; m < 4; ++m) _Pragma("unroll") for (int k = 0; k < 2; ++k) dst[m][k] = *(const PG8_LAS bf16x8*)(lds + PG8_SA(b, h) + aoff + m * 2048 + k * 1024); } while (0)
; #define PG8_MMA(ai, bj, At, Bt) do { __builtin_amdgcn_s_setprio(1); _Pragma("unroll") for (int m = 0; m < 4; ++m) _Pragma("unroll") for (int n = 0; n < 2; ++n) _Pragma("unroll") for (int k = 0; k < 2; ++k) \
;         acc[ai][bj][m][n] = __builtin_amdgcn_mfma_f32_16x16x32_bf16(Bt[n][k], At[m][k], acc[ai][bj][m][n], 0, 0, 0); __builtin_amdgcn_s_setprio(0); } while (0)
; #define PG8_WAIT_V(n) asm volatile("s_waitcnt vmcnt(" #n ")" ::: "memory")
; #define PG8_WAIT_L(n) asm volatile("s_waitcnt lgkmcnt(" #n ")" ::: "memory")
; #define PG8_BAR __builtin_amdgcn_s_barrier()
; #define PG8_SCHED __builtin_amdgcn_sched_barrier(0)
; template <class Epi, class Sched, bool ALIGN_EPI = false, bool SP2 = false>
; __device__ __forceinline__ void gemm_phase(PG8_LAS unsigned char* lds, const Gemm g, const Sched& S, const Epi& E, int tid_in) {
;     ...
;             PG8_LDA(At, 1, 1); PG8_STAGE(PG8_SB(1, 0), b3, voffB); PG8_STAGE(PG8_SB(1, 1), b3 + hstep, voffB); PG8_STAGE(PG8_SA(1, 0), a3, voffA);
;             PG8_WAIT_V(8); PG8_WAIT_L(0); PG8_BAR; PG8_MMA(1, 0, At, B0); PG8_MMA(1, 1, At, B1); PG8_BAR; PG8_SCHED;
;     ...
;         if constexpr (ALIGN_EPI) { if (wr == 0) PG8_BAR; }
	v_mfma_f32_16x16x32_bf16 v[82:85], v[158:161], v[232:235], v[82:85]
	s_setprio 0
	s_mov_b32 m0, s64
	v_lshl_add_u64 v[180:181], v[218:219], 0, s[48:49]
	ds_read_b128 v[182:185], v214 offset:49152
	ds_read_b128 v[194:197], v214 offset:50176
	ds_read_b128 v[198:201], v214 offset:51200
	ds_read_b128 v[202:205], v214 offset:52224
	ds_read_b128 v[206:209], v214 offset:53248
	ds_read_b128 v[210:213], v214 offset:54272
	ds_read_b128 v[226:229], v214 offset:55296
	ds_read_b128 v[232:235], v214 offset:56320
	global_load_lds_dwordx4 v[180:181], off
	v_lshl_add_u64 v[180:181], v[250:251], 0, s[48:49]
	s_mov_b32 m0, s65
	v_lshl_add_u64 v[178:179], v[178:179], 0, s[48:49]
	global_load_lds_dwordx4 v[180:181], off
	v_lshl_add_u64 v[180:181], v[236:237], 0, s[48:49]
	s_mov_b32 m0, s61
	s_nop 0
	global_load_lds_dwordx4 v[180:181], off
	v_lshl_add_u64 v[180:181], v[238:239], 0, s[48:49]
	s_mov_b32 m0, s62
	s_nop 0
	global_load_lds_dwordx4 v[180:181], off
	v_lshl_add_u64 v[180:181], v[240:241], 0, s[48:49]
	s_mov_b32 m0, s72
	s_nop 0
	global_load_lds_dwordx4 v[180:181], off
	s_mov_b32 m0, s73
	s_nop 0
	global_load_lds_dwordx4 v[178:179], off
	s_waitcnt vmcnt(8)
	s_waitcnt lgkmcnt(0)
	s_barrier
	s_setprio 1
	s_waitcnt lgkmcnt(0)
	v_mfma_f32_16x16x32_bf16 v[76:79], v[52:55], v[182:185], v[76:79]
	v_mfma_f32_16x16x32_bf16 v[72:75], v[64:67], v[182:185], v[72:75]
	v_mfma_f32_16x16x32_bf16 v[56:59], v[52:55], v[198:201], v[56:59]
	v_mfma_f32_16x16x32_bf16 v[48:51], v[64:67], v[198:201], v[48:51]
	v_mfma_f32_16x16x32_bf16 v[28:31], v[52:55], v[206:209], v[28:31]
	v_mfma_f32_16x16x32_bf16 v[24:27], v[64:67], v[206:209], v[24:27]
	v_mfma_f32_16x16x32_bf16 v[12:15], v[52:55], v[226:229], v[12:15]
	v_mfma_f32_16x16x32_bf16 v[8:11], v[64:67], v[226:229], v[8:11]
	v_mfma_f32_16x16x32_bf16 v[76:79], v[60:63], v[194:197], v[76:79]
	v_mfma_f32_16x16x32_bf16 v[72:75], v[68:71], v[194:197], v[72:75]
	v_mfma_f32_16x16x32_bf16 v[56:59], v[60:63], v[202:205], v[56:59]
	v_mfma_f32_16x16x32_bf16 v[48:51], v[68:71], v[202:205], v[48:51]
	v_mfma_f32_16x16x32_bf16 v[28:31], v[60:63], v[210:213], v[28:31]
	v_mfma_f32_16x16x32_bf16 v[24:27], v[68:71], v[210:213], v[24:27]
	v_mfma_f32_16x16x32_bf16 v[12:15], v[60:63], v[232:235], v[12:15]
	v_mfma_f32_16x16x32_bf16 v[8:11], v[68:71], v[232:235], v[8:11]
	s_setprio 0
	s_setprio 1
	v_mfma_f32_16x16x32_bf16 v[40:43], v[146:149], v[182:185], v[40:43]
	v_mfma_f32_16x16x32_bf16 v[68:71], v[150:153], v[194:197], v[40:43]
	v_mfma_f32_16x16x32_bf16 v[40:43], v[154:157], v[182:185], v[44:47]
	v_mfma_f32_16x16x32_bf16 v[36:39], v[146:149], v[198:201], v[36:39]
	v_mfma_f32_16x16x32_bf16 v[32:35], v[154:157], v[198:201], v[32:35]
	v_mfma_f32_16x16x32_bf16 v[20:23], v[146:149], v[206:209], v[20:23]
	v_mfma_f32_16x16x32_bf16 v[16:19], v[154:157], v[206:209], v[16:19]
	v_mfma_f32_16x16x32_bf16 v[4:7], v[146:149], v[226:229], v[4:7]
	v_mfma_f32_16x16x32_bf16 v[0:3], v[154:157], v[226:229], v[0:3]
	v_mfma_f32_16x16x32_bf16 v[64:67], v[158:161], v[194:197], v[40:43]
	v_mfma_f32_16x16x32_bf16 v[36:39], v[150:153], v[202:205], v[36:39]
	v_mfma_f32_16x16x32_bf16 v[32:35], v[158:161], v[202:205], v[32:35]
	v_mfma_f32_16x16x32_bf16 v[20:23], v[150:153], v[210:213], v[20:23]
	v_mfma_f32_16x16x32_bf16 v[16:19], v[158:161], v[210:213], v[16:19]
	v_mfma_f32_16x16x32_bf16 v[4:7], v[150:153], v[232:235], v[4:7]
	s_barrier
	v_mfma_f32_16x16x32_bf16 v[0:3], v[158:161], v[232:235], v[0:3]
	s_setprio 0
	s_add_u32 s40, s40, 0x100
	s_addc_u32 s41, s41, 0
	s_add_u32 s26, s26, 0x100
	s_addc_u32 s27, s27, 0
	s_cmp_ge_u32 s44, s66
	s_mov_b32 s42, s44
	s_cbranch_scc0 .LBB0_508
	s_and_b64 vcc, exec, s[78:79]
	s_cbranch_vccz .LBB0_511
	s_barrier
	s_setprio 1

; #define PG8_STAGE(bufoff, gbase, voff) do { _Pragma("unroll") for (int _i = 0; _i < 2; ++_i) \
;         __builtin_amdgcn_global_load_lds((const unsigned*)((const char*)(gbase) + (voff)[_i]), (PG8_LAS unsigned*)(lds + (bufoff) + ldsw + _i * 8192), 16, 0, 0); } while (0)
; #define PG8_LDA(dst, b, h) do { _Pragma("unroll") for (int m = 0; m < 4; ++m) _Pragma("unroll") for (int k = 0; k < 2; ++k) dst[m][k] = *(const PG8_LAS bf16x8*)(lds + PG8_SA(b, h) + aoff + m * 2048 + k * 1024); } while (0)
; #define PG8_LDB(dst, b, h) do { _Pragma("unroll") for (int n = 0; n < 2; ++n) _Pragma("unroll") for (int k = 0; k < 2; ++k) dst[n][k] = *(const PG8_LAS bf16x8*)(lds + PG8_SB(b, h) + boff + n * 2048 + k * 1024); } while (0)
; #define PG8_MMA(ai, bj, At, Bt) do { __builtin_amdgcn_s_setprio(1); _Pragma("unroll") for (int m = 0; m < 4; ++m) _Pragma("unroll") for (int n = 0; n < 2; ++n) _Pragma("unroll") for (int k = 0; k < 2; ++k) \
;         acc[ai][bj][m][n] = __builtin_amdgcn_mfma_f32_16x16x32_bf16(Bt[n][k], At[m][k], acc[ai][bj][m][n], 0, 0, 0); __builtin_amdgcn_s_setprio(0); } while (0)
; #define PG8_WAIT_V(n) asm volatile("s_waitcnt vmcnt(" #n ")" ::: "memory")
; #define PG8_WAIT_L(n) asm volatile("s_waitcnt lgkmcnt(" #n ")" ::: "memory")
; #define PG8_BAR __builtin_amdgcn_s_barrier()
; #define PG8_SCHED __builtin_amdgcn_sched_barrier(0)
; template <class Epi, class Sched, bool ALIGN_EPI = false, bool SP2 = false>
; __device__ __forceinline__ void gemm_phase(PG8_LAS unsigned char* lds, const Gemm g, const Sched& S, const Epi& E, int tid_in) {
;     ...
;             PG8_LDB(B0, 0, 0); PG8_LDB(B1, 0, 1); PG8_SCHED; PG8_LDA(At, 0, 0); PG8_STAGE(PG8_SA(1, 1), a1 + hstep, voffA);
;             PG8_WAIT_V(8); PG8_WAIT_L(0); PG8_BAR; PG8_MMA(0, 0, At, B0); PG8_MMA(0, 1, At, B1); PG8_BAR; PG8_SCHED;
;             PG8_LDA(At, 0, 1); PG8_STAGE(PG8_SB(0, 0), b2, voffB); PG8_STAGE(PG8_SB(0, 1), b2 + hstep, voffB); PG8_STAGE(PG8_SA(0, 0), a2, voffA);
;             PG8_WAIT_V(8); PG8_WAIT_L(0); PG8_BAR; PG8_MMA(1, 0, At, B0); PG8_MMA(1, 1, At, B1); PG8_BAR; PG8_SCHED;
.LBB0_780:
	v_or_b32_e32 v142, 0x10000, v145
	v_add_u32_e32 v143, 0x10400, v145
	ds_read_b128 v[148:151], v142
	ds_read_b128 v[152:155], v143
	v_add_u32_e32 v142, 0x10800, v145
	v_add_u32_e32 v143, 0x10c00, v145
	ds_read_b128 v[156:159], v142
	ds_read_b128 v[160:163], v143
	v_or_b32_e32 v142, 0x14000, v145
	v_add_u32_e32 v143, 0x14400, v145
	ds_read_b128 v[164:167], v142
	ds_read_b128 v[168:171], v143
	v_add_u32_e32 v142, 0x14800, v145
	v_add_u32_e32 v143, 0x14c00, v145
	ds_read_b128 v[172:175], v142
	ds_read_b128 v[194:197], v143
	s_add_u32 s70, s68, 0xfffc0080
	s_addc_u32 s71, s69, -1
	s_cmp_eq_u32 s82, 12
	s_cselect_b32 s73, s45, s71
	s_cselect_b32 s72, s78, s70
	s_cselect_b32 s71, s43, s81
	s_cselect_b32 s70, s79, s80
	v_lshl_add_u64 v[142:143], s[68:69], 0, v[138:139]
	s_add_i32 m0, s22, 0xc000
	ds_read_b128 v[198:201], v144
	ds_read_b128 v[202:205], v144 offset:1024
	ds_read_b128 v[206:209], v144 offset:2048
	ds_read_b128 v[210:213], v144 offset:3072
	ds_read_b128 v[214:217], v144 offset:4096
	ds_read_b128 v[248:251], v144 offset:5120
	ds_read_b128 v[232:235], v144 offset:6144
	ds_read_b128 v[226:229], v144 offset:7168
	global_load_lds_dwordx4 v[142:143], off
	v_lshl_add_u64 v[142:143], s[68:69], 0, v[140:141]
	s_add_i32 m0, s22, 0xe000
	s_nop 0
	global_load_lds_dwordx4 v[142:143], off
	s_waitcnt vmcnt(8)
	s_waitcnt lgkmcnt(0)
	s_barrier
	s_setprio 1
	s_waitcnt lgkmcnt(0)
	v_mfma_f32_16x16x32_bf16 v[126:129], v[148:151], v[198:201], v[126:129]
	v_mfma_f32_16x16x32_bf16 v[118:121], v[156:159], v[198:201], v[118:121]
	v_mfma_f32_16x16x32_bf16 v[110:113], v[148:151], v[206:209], v[110:113]
	v_mfma_f32_16x16x32_bf16 v[102:105], v[156:159], v[206:209], v[102:105]
	v_mfma_f32_16x16x32_bf16 v[94:97], v[148:151], v[214:217], v[94:97]
	v_mfma_f32_16x16x32_bf16 v[86:89], v[156:159], v[214:217], v[86:89]
	v_mfma_f32_16x16x32_bf16 v[76:79], v[148:151], v[232:235], v[76:79]
	v_mfma_f32_16x16x32_bf16 v[68:71], v[156:159], v[232:235], v[68:71]
	v_mfma_f32_16x16x32_bf16 v[126:129], v[152:155], v[202:205], v[126:129]
	v_mfma_f32_16x16x32_bf16 v[118:121], v[160:163], v[202:205], v[118:121]
	v_mfma_f32_16x16x32_bf16 v[110:113], v[152:155], v[210:213], v[110:113]
	v_mfma_f32_16x16x32_bf16 v[102:105], v[160:163], v[210:213], v[102:105]
	v_mfma_f32_16x16x32_bf16 v[94:97], v[152:155], v[248:251], v[94:97]
	v_mfma_f32_16x16x32_bf16 v[86:89], v[160:163], v[248:251], v[86:89]
	v_mfma_f32_16x16x32_bf16 v[76:79], v[152:155], v[226:229], v[76:79]
	v_mfma_f32_16x16x32_bf16 v[68:71], v[160:163], v[226:229], v[68:71]
	s_setprio 0
	s_setprio 1
	v_mfma_f32_16x16x32_bf16 v[122:125], v[164:167], v[198:201], v[122:125]
	v_mfma_f32_16x16x32_bf16 v[114:117], v[172:175], v[198:201], v[114:117]
	v_mfma_f32_16x16x32_bf16 v[106:109], v[164:167], v[206:209], v[106:109]
	v_mfma_f32_16x16x32_bf16 v[98:101], v[172:175], v[206:209], v[98:101]
	v_mfma_f32_16x16x32_bf16 v[90:93], v[164:167], v[214:217], v[90:93]
	v_mfma_f32_16x16x32_bf16 v[82:85], v[172:175], v[214:217], v[82:85]
	v_mfma_f32_16x16x32_bf16 v[72:75], v[164:167], v[232:235], v[72:75]
	v_mfma_f32_16x16x32_bf16 v[64:67], v[172:175], v[232:235], v[64:67]
	v_mfma_f32_16x16x32_bf16 v[122:125], v[168:171], v[202:205], v[122:125]
	v_mfma_f32_16x16x32_bf16 v[114:117], v[194:197], v[202:205], v[114:117]
	v_mfma_f32_16x16x32_bf16 v[106:109], v[168:171], v[210:213], v[106:109]
	v_mfma_f32_16x16x32_bf16 v[98:101], v[194:197], v[210:213], v[98:101]
	v_mfma_f32_16x16x32_bf16 v[90:93], v[168:171], v[248:251], v[90:93]
	v_mfma_f32_16x16x32_bf16 v[82:85], v[194:197], v[248:251], v[82:85]
	v_mfma_f32_16x16x32_bf16 v[72:75], v[168:171], v[226:229], v[72:75]
	s_barrier
	v_mfma_f32_16x16x32_bf16 v[64:67], v[194:197], v[226:229], v[64:67]
	s_setprio 0
	s_mov_b32 m0, s24
	v_lshl_add_u64 v[142:143], s[70:71], 0, v[134:135]
	s_add_u32 s84, s70, 0x40000
	ds_read_b128 v[198:201], v144 offset:16384
	ds_read_b128 v[202:205], v144 offset:17408
	ds_read_b128 v[206:209], v144 offset:18432
	ds_read_b128 v[210:213], v144 offset:19456
	ds_read_b128 v[214:217], v144 offset:20480
	ds_read_b128 v[226:229], v144 offset:21504
	ds_read_b128 v[232:235], v144 offset:22528
	ds_read_b128 v[248:251], v144 offset:23552
	global_load_lds_dwordx4 v[142:143], off
	v_lshl_add_u64 v[176:177], s[70:71], 0, v[130:131]
	s_mov_b32 m0, s25
	s_addc_u32 s85, s71, 0
	global_load_lds_dwordx4 v[176:177], off
	v_lshl_add_u64 v[182:183], s[84:85], 0, v[134:135]
	s_mov_b32 m0, s26
	v_lshl_add_u64 v[184:185], s[72:73], 0, v[132:133]
	global_load_lds_dwordx4 v[182:183], off
	v_lshl_add_u64 v[182:183], s[84:85], 0, v[130:131]
	s_mov_b32 m0, s27
	s_nop 0
	global_load_lds_dwordx4 v[182:183], off
	v_lshl_add_u64 v[182:183], s[72:73], 0, v[136:137]
	s_mov_b32 m0, s22
	s_nop 0
	global_load_lds_dwordx4 v[182:183], off
	s_mov_b32 m0, s29
	s_nop 0
	global_load_lds_dwordx4 v[184:185], off
	s_waitcnt vmcnt(8)
	s_waitcnt lgkmcnt(0)
	s_barrier
; #define PG8_STAGE(bufoff, gbase, voff) do { _Pragma("unroll") for (int _i = 0; _i < 2; ++_i) \
;         __builtin_amdgcn_global_load_lds((const unsigned*)((const char*)(gbase) + (voff)[_i]), (PG8_LAS unsigned*)(lds + (bufoff) + ldsw + _i * 8192), 16, 0, 0); } while (0)
; #define PG8_LDA(dst, b, h) do { _Pragma("unroll") for (int m = 0; m < 4; ++m) _Pragma("unroll") for (int k = 0; k < 2; ++k) dst[m][k] = *(const PG8_LAS bf16x8*)(lds + PG8_SA(b, h) + aoff + m * 2048 + k * 1024); } while (0)
; #define PG8_LDB(dst, b, h) do { _Pragma("unroll") for (int n = 0; n < 2; ++n) _Pragma("unroll") for (int k = 0; k < 2; ++k) dst[n][k] = *(const PG8_LAS bf16x8*)(lds + PG8_SB(b, h) + boff + n * 2048 + k * 1024); } while (0)
; #define PG8_MMA(ai, bj, At, Bt) do { __builtin_amdgcn_s_setprio(1); _Pragma("unroll") for (int m = 0; m < 4; ++m) _Pragma("unroll") for (int n = 0; n < 2; ++n) _Pragma("unroll") for (int k = 0; k < 2; ++k) \
;         acc[ai][bj][m][n] = __builtin_amdgcn_mfma_f32_16x16x32_bf16(Bt[n][k], At[m][k], acc[ai][bj][m][n], 0, 0, 0); __builtin_amdgcn_s_setprio(0); } while (0)
; #define PG8_WAIT_V(n) asm volatile("s_waitcnt vmcnt(" #n ")" ::: "memory")
; #define PG8_WAIT_L(n) asm volatile("s_waitcnt lgkmcnt(" #n ")" ::: "memory")
; #define PG8_BAR __builtin_amdgcn_s_barrier()
; #define PG8_SCHED __builtin_amdgcn_sched_barrier(0)
; template <class Epi, class Sched, bool ALIGN_EPI = false, bool SP2 = false>
; __device__ __forceinline__ void gemm_phase(PG8_LAS unsigned char* lds, const Gemm g, const Sched& S, const Epi& E, int tid_in) {
;     ...
;             PG8_WAIT_V(8); PG8_WAIT_L(0); PG8_BAR; PG8_MMA(1, 0, At, B0); PG8_MMA(1, 1, At, B1); PG8_BAR; PG8_SCHED;
;             PG8_LDB(B0, 1, 0); PG8_LDB(B1, 1, 1); PG8_SCHED; PG8_LDA(At, 1, 0); PG8_STAGE(PG8_SA(0, 1), a2 + hstep, voffA);
;             PG8_WAIT_V(8); PG8_WAIT_L(0); PG8_BAR; PG8_MMA(0, 0, At, B0); PG8_MMA(0, 1, At, B1); PG8_BAR; PG8_SCHED;
	s_setprio 1
	s_waitcnt lgkmcnt(0)
	v_mfma_f32_16x16x32_bf16 v[60:63], v[148:151], v[198:201], v[60:63]
	v_mfma_f32_16x16x32_bf16 v[52:55], v[156:159], v[198:201], v[52:55]
	v_mfma_f32_16x16x32_bf16 v[44:47], v[148:151], v[206:209], v[44:47]
	v_mfma_f32_16x16x32_bf16 v[36:39], v[156:159], v[206:209], v[36:39]
	v_mfma_f32_16x16x32_bf16 v[28:31], v[148:151], v[214:217], v[28:31]
	v_mfma_f32_16x16x32_bf16 v[20:23], v[156:159], v[214:217], v[20:23]
	v_mfma_f32_16x16x32_bf16 v[12:15], v[148:151], v[232:235], v[12:15]
	v_mfma_f32_16x16x32_bf16 v[4:7], v[156:159], v[232:235], v[4:7]
	v_mfma_f32_16x16x32_bf16 v[60:63], v[152:155], v[202:205], v[60:63]
	v_mfma_f32_16x16x32_bf16 v[52:55], v[160:163], v[202:205], v[52:55]
	v_mfma_f32_16x16x32_bf16 v[44:47], v[152:155], v[210:213], v[44:47]
	v_mfma_f32_16x16x32_bf16 v[36:39], v[160:163], v[210:213], v[36:39]
	v_mfma_f32_16x16x32_bf16 v[28:31], v[152:155], v[226:229], v[28:31]
	v_mfma_f32_16x16x32_bf16 v[20:23], v[160:163], v[226:229], v[20:23]
	v_mfma_f32_16x16x32_bf16 v[12:15], v[152:155], v[248:251], v[12:15]
	v_mfma_f32_16x16x32_bf16 v[4:7], v[160:163], v[248:251], v[4:7]
	s_setprio 0
	s_setprio 1
	v_mfma_f32_16x16x32_bf16 v[56:59], v[164:167], v[198:201], v[56:59]
	v_mfma_f32_16x16x32_bf16 v[48:51], v[172:175], v[198:201], v[48:51]
	v_mfma_f32_16x16x32_bf16 v[40:43], v[164:167], v[206:209], v[40:43]
	v_mfma_f32_16x16x32_bf16 v[32:35], v[172:175], v[206:209], v[32:35]
	v_mfma_f32_16x16x32_bf16 v[24:27], v[164:167], v[214:217], v[24:27]
	v_mfma_f32_16x16x32_bf16 v[16:19], v[172:175], v[214:217], v[16:19]
	v_mfma_f32_16x16x32_bf16 v[8:11], v[164:167], v[232:235], v[8:11]
	v_mfma_f32_16x16x32_bf16 v[0:3], v[172:175], v[232:235], v[0:3]
	v_mfma_f32_16x16x32_bf16 v[56:59], v[168:171], v[202:205], v[56:59]
	v_mfma_f32_16x16x32_bf16 v[48:51], v[194:197], v[202:205], v[48:51]
	v_mfma_f32_16x16x32_bf16 v[40:43], v[168:171], v[210:213], v[40:43]
	v_mfma_f32_16x16x32_bf16 v[32:35], v[194:197], v[210:213], v[32:35]
	v_mfma_f32_16x16x32_bf16 v[24:27], v[168:171], v[226:229], v[24:27]
	v_mfma_f32_16x16x32_bf16 v[16:19], v[194:197], v[226:229], v[16:19]
	v_mfma_f32_16x16x32_bf16 v[8:11], v[168:171], v[248:251], v[8:11]
	s_barrier
	v_mfma_f32_16x16x32_bf16 v[0:3], v[194:197], v[248:251], v[0:3]
	s_setprio 0
	v_or_b32_e32 v148, 0x18000, v145
	v_add_u32_e32 v152, 0x18400, v145
	v_add_u32_e32 v156, 0x18800, v145
	v_add_u32_e32 v160, 0x18c00, v145
	v_or_b32_e32 v164, 0x1c000, v145
	v_add_u32_e32 v168, 0x1c400, v145
	v_add_u32_e32 v172, 0x1c800, v145
	ds_read_b128 v[148:151], v148
	ds_read_b128 v[152:155], v152
	ds_read_b128 v[156:159], v156
	ds_read_b128 v[160:163], v160
	ds_read_b128 v[164:167], v164
	ds_read_b128 v[168:171], v168
	v_add_u32_e32 v178, 0x1cc00, v145
	ds_read_b128 v[172:175], v172
	ds_read_b128 v[194:197], v178
	s_add_u32 s72, s72, 0x40000
	s_addc_u32 s73, s73, 0
	s_mov_b32 m0, s31
	v_lshl_add_u64 v[218:219], s[72:73], 0, v[136:137]
	ds_read_b128 v[198:201], v144 offset:32768
	ds_read_b128 v[202:205], v144 offset:33792
	ds_read_b128 v[206:209], v144 offset:34816
	ds_read_b128 v[210:213], v144 offset:35840
	ds_read_b128 v[214:217], v144 offset:36864
	ds_read_b128 v[226:229], v144 offset:37888
	ds_read_b128 v[232:235], v144 offset:38912
	ds_read_b128 v[248:251], v144 offset:39936
	global_load_lds_dwordx4 v[218:219], off
	v_lshl_add_u64 v[218:219], s[72:73], 0, v[132:133]
	s_mov_b32 m0, s57
	s_nop 0
	global_load_lds_dwordx4 v[218:219], off
	s_waitcnt vmcnt(8)
	s_waitcnt lgkmcnt(0)
	s_barrier
	s_setprio 1
	s_waitcnt lgkmcnt(0)
	v_mfma_f32_16x16x32_bf16 v[126:129], v[148:151], v[198:201], v[126:129]
	v_mfma_f32_16x16x32_bf16 v[118:121], v[156:159], v[198:201], v[118:121]
	v_mfma_f32_16x16x32_bf16 v[110:113], v[148:151], v[206:209], v[110:113]
	v_mfma_f32_16x16x32_bf16 v[102:105], v[156:159], v[206:209], v[102:105]
	v_mfma_f32_16x16x32_bf16 v[94:97], v[148:151], v[214:217], v[94:97]
	v_mfma_f32_16x16x32_bf16 v[86:89], v[156:159], v[214:217], v[86:89]
	v_mfma_f32_16x16x32_bf16 v[76:79], v[148:151], v[232:235], v[76:79]
	v_mfma_f32_16x16x32_bf16 v[68:71], v[156:159], v[232:235], v[68:71]
	v_mfma_f32_16x16x32_bf16 v[126:129], v[152:155], v[202:205], v[126:129]
	v_mfma_f32_16x16x32_bf16 v[118:121], v[160:163], v[202:205], v[118:121]
	v_mfma_f32_16x16x32_bf16 v[110:113], v[152:155], v[210:213], v[110:113]
	v_mfma_f32_16x16x32_bf16 v[102:105], v[160:163], v[210:213], v[102:105]
	v_mfma_f32_16x16x32_bf16 v[94:97], v[152:155], v[226:229], v[94:97]
	v_mfma_f32_16x16x32_bf16 v[86:89], v[160:163], v[226:229], v[86:89]
	v_mfma_f32_16x16x32_bf16 v[76:79], v[152:155], v[248:251], v[76:79]
	v_mfma_f32_16x16x32_bf16 v[68:71], v[160:163], v[248:251], v[68:71]
	s_setprio 0
	s_setprio 1
	v_mfma_f32_16x16x32_bf16 v[122:125], v[164:167], v[198:201], v[122:125]
	v_mfma_f32_16x16x32_bf16 v[114:117], v[172:175], v[198:201], v[114:117]
	v_mfma_f32_16x16x32_bf16 v[106:109], v[164:167], v[206:209], v[106:109]
	v_mfma_f32_16x16x32_bf16 v[98:101], v[172:175], v[206:209], v[98:101]
	v_mfma_f32_16x16x32_bf16 v[90:93], v[164:167], v[214:217], v[90:93]
	v_mfma_f32_16x16x32_bf16 v[82:85], v[172:175], v[214:217], v[82:85]
	v_mfma_f32_16x16x32_bf16 v[72:75], v[164:167], v[232:235], v[72:75]
	v_mfma_f32_16x16x32_bf16 v[64:67], v[172:175], v[232:235], v[64:67]
	v_mfma_f32_16x16x32_bf16 v[122:125], v[168:171], v[202:205], v[122:125]
	v_mfma_f32_16x16x32_bf16 v[114:117], v[194:197], v[202:205], v[114:117]
	v_mfma_f32_16x16x32_bf16 v[106:109], v[168:171], v[210:213], v[106:109]
	v_mfma_f32_16x16x32_bf16 v[98:101], v[194:197], v[210:213], v[98:101]
	v_mfma_f32_16x16x32_bf16 v[90:93], v[168:171], v[226:229], v[90:93]
	v_mfma_f32_16x16x32_bf16 v[82:85], v[194:197], v[226:229], v[82:85]
	v_mfma_f32_16x16x32_bf16 v[72:75], v[168:171], v[248:251], v[72:75]
	s_barrier
; #define PG8_STAGE(bufoff, gbase, voff) do { _Pragma("unroll") for (int _i = 0; _i < 2; ++_i) \
;         __builtin_amdgcn_global_load_lds((const unsigned*)((const char*)(gbase) + (voff)[_i]), (PG8_LAS unsigned*)(lds + (bufoff) + ldsw + _i * 8192), 16, 0, 0); } while (0)
; #define PG8_LDA(dst, b, h) do { _Pragma("unroll") for (int m = 0; m < 4; ++m) _Pragma("unroll") for (int k = 0; k < 2; ++k) dst[m][k] = *(const PG8_LAS bf16x8*)(lds + PG8_SA(b, h) + aoff + m * 2048 + k * 1024); } while (0)
; #define PG8_MMA(ai, bj, At, Bt) do { __builtin_amdgcn_s_setprio(1); _Pragma("unroll") for (int m = 0; m < 4; ++m) _Pragma("unroll") for (int n = 0; n < 2; ++n) _Pragma("unroll") for (int k = 0; k < 2; ++k) \
;         acc[ai][bj][m][n] = __builtin_amdgcn_mfma_f32_16x16x32_bf16(Bt[n][k], At[m][k], acc[ai][bj][m][n], 0, 0, 0); __builtin_amdgcn_s_setprio(0); } while (0)
; #define PG8_WAIT_V(n) asm volatile("s_waitcnt vmcnt(" #n ")" ::: "memory")
; #define PG8_WAIT_L(n) asm volatile("s_waitcnt lgkmcnt(" #n ")" ::: "memory")
; #define PG8_BAR __builtin_amdgcn_s_barrier()
; #define PG8_SCHED __builtin_amdgcn_sched_barrier(0)
; template <class Epi, class Sched, bool ALIGN_EPI = false, bool SP2 = false>
; __device__ __forceinline__ void gemm_phase(PG8_LAS unsigned char* lds, const Gemm g, const Sched& S, const Epi& E, int tid_in) {
;     ...
;             PG8_LDA(At, 1, 1); PG8_STAGE(PG8_SB(1, 0), b3, voffB); PG8_STAGE(PG8_SB(1, 1), b3 + hstep, voffB); PG8_STAGE(PG8_SA(1, 0), a3, voffA);
;             PG8_WAIT_V(8); PG8_WAIT_L(0); PG8_BAR; PG8_MMA(1, 0, At, B0); PG8_MMA(1, 1, At, B1); PG8_BAR; PG8_SCHED;
;     ...
;         if constexpr (ALIGN_EPI) { if (wr == 0) PG8_BAR; }
	v_mfma_f32_16x16x32_bf16 v[64:67], v[194:197], v[248:251], v[64:67]
	s_setprio 0
	s_mov_b32 m0, s58
	v_lshl_add_u64 v[142:143], v[142:143], 0, s[48:49]
	s_add_u32 s70, s70, 0x40080
	ds_read_b128 v[198:201], v144 offset:49152
	ds_read_b128 v[202:205], v144 offset:50176
	ds_read_b128 v[206:209], v144 offset:51200
	ds_read_b128 v[210:213], v144 offset:52224
	ds_read_b128 v[214:217], v144 offset:53248
	ds_read_b128 v[226:229], v144 offset:54272
	ds_read_b128 v[232:235], v144 offset:55296
	ds_read_b128 v[248:251], v144 offset:56320
	global_load_lds_dwordx4 v[142:143], off
	v_lshl_add_u64 v[142:143], v[176:177], 0, s[48:49]
	s_mov_b32 m0, s59
	s_addc_u32 s71, s71, 0
	global_load_lds_dwordx4 v[142:143], off
	v_lshl_add_u64 v[142:143], s[70:71], 0, v[134:135]
	s_mov_b32 m0, s63
	s_nop 0
	global_load_lds_dwordx4 v[142:143], off
	v_lshl_add_u64 v[142:143], s[70:71], 0, v[130:131]
	s_mov_b32 m0, s67
	s_nop 0
	global_load_lds_dwordx4 v[142:143], off
	v_lshl_add_u64 v[142:143], v[182:183], 0, s[48:49]
	s_mov_b32 m0, s61
	s_nop 0
	global_load_lds_dwordx4 v[142:143], off
	v_lshl_add_u64 v[142:143], v[184:185], 0, s[48:49]
	s_mov_b32 m0, s62
	s_nop 0
	global_load_lds_dwordx4 v[142:143], off
	s_waitcnt vmcnt(8)
	s_waitcnt lgkmcnt(0)
	s_barrier
	s_setprio 1
	s_waitcnt lgkmcnt(0)
	v_mfma_f32_16x16x32_bf16 v[60:63], v[148:151], v[198:201], v[60:63]
	v_mfma_f32_16x16x32_bf16 v[52:55], v[156:159], v[198:201], v[52:55]
	v_mfma_f32_16x16x32_bf16 v[44:47], v[148:151], v[206:209], v[44:47]
	v_mfma_f32_16x16x32_bf16 v[36:39], v[156:159], v[206:209], v[36:39]
	v_mfma_f32_16x16x32_bf16 v[28:31], v[148:151], v[214:217], v[28:31]
	v_mfma_f32_16x16x32_bf16 v[20:23], v[156:159], v[214:217], v[20:23]
	v_mfma_f32_16x16x32_bf16 v[12:15], v[148:151], v[232:235], v[12:15]
	v_mfma_f32_16x16x32_bf16 v[4:7], v[156:159], v[232:235], v[4:7]
	v_mfma_f32_16x16x32_bf16 v[60:63], v[152:155], v[202:205], v[60:63]
	v_mfma_f32_16x16x32_bf16 v[52:55], v[160:163], v[202:205], v[52:55]
	v_mfma_f32_16x16x32_bf16 v[44:47], v[152:155], v[210:213], v[44:47]
	v_mfma_f32_16x16x32_bf16 v[36:39], v[160:163], v[210:213], v[36:39]
	v_mfma_f32_16x16x32_bf16 v[28:31], v[152:155], v[226:229], v[28:31]
	v_mfma_f32_16x16x32_bf16 v[20:23], v[160:163], v[226:229], v[20:23]
	v_mfma_f32_16x16x32_bf16 v[12:15], v[152:155], v[248:251], v[12:15]
	v_mfma_f32_16x16x32_bf16 v[4:7], v[160:163], v[248:251], v[4:7]
	s_setprio 0
	s_setprio 1
	v_mfma_f32_16x16x32_bf16 v[56:59], v[164:167], v[198:201], v[56:59]
	v_mfma_f32_16x16x32_bf16 v[48:51], v[172:175], v[198:201], v[48:51]
	v_mfma_f32_16x16x32_bf16 v[40:43], v[164:167], v[206:209], v[40:43]
	v_mfma_f32_16x16x32_bf16 v[32:35], v[172:175], v[206:209], v[32:35]
	v_mfma_f32_16x16x32_bf16 v[24:27], v[164:167], v[214:217], v[24:27]
	v_mfma_f32_16x16x32_bf16 v[16:19], v[172:175], v[214:217], v[16:19]
	v_mfma_f32_16x16x32_bf16 v[8:11], v[164:167], v[232:235], v[8:11]
	v_mfma_f32_16x16x32_bf16 v[0:3], v[172:175], v[232:235], v[0:3]
	v_mfma_f32_16x16x32_bf16 v[56:59], v[168:171], v[202:205], v[56:59]
	v_mfma_f32_16x16x32_bf16 v[48:51], v[194:197], v[202:205], v[48:51]
	v_mfma_f32_16x16x32_bf16 v[40:43], v[168:171], v[210:213], v[40:43]
	v_mfma_f32_16x16x32_bf16 v[32:35], v[194:197], v[210:213], v[32:35]
	v_mfma_f32_16x16x32_bf16 v[24:27], v[168:171], v[226:229], v[24:27]
	v_mfma_f32_16x16x32_bf16 v[16:19], v[194:197], v[226:229], v[16:19]
	v_mfma_f32_16x16x32_bf16 v[8:11], v[168:171], v[248:251], v[8:11]
	s_barrier
	v_mfma_f32_16x16x32_bf16 v[0:3], v[194:197], v[248:251], v[0:3]
	s_setprio 0
	s_add_i32 s82, s82, 2
	s_add_u32 s68, s68, 0x100
	s_addc_u32 s69, s69, 0
	s_add_u32 s80, s80, 0x100
	s_addc_u32 s81, s81, 0
	s_cmp_gt_u32 s82, 13
	s_cbranch_scc0 .LBB0_780
	s_and_b64 vcc, exec, s[40:41]
	s_cbranch_vccz .LBB0_783
	s_barrier
	s_setprio 1
